# wave-sum butterflies: xor-1/2/4/8 ds_swizzle round trips replaced by DPP adds (quad_perm / row_half_mirror / row_mirror) in the QK-norm phase and attention epilogues
# speedup vs baseline: 1.0070x; 1.0070x over previous
; __device__ __forceinline__ int ltid() { int t = threadIdx.x; asm volatile("" : "+v"(t)); return t; }
; __device__ __forceinline__ float bf_lo(unsigned w) { return __uint_as_float(w << 16); }
; __device__ __forceinline__ float bf_hi(unsigned w) { return __uint_as_float(w & 0xffff0000u); }
; __device__ __forceinline__ int crow(int r, int hi) { return (r & 3) + 8 * (r >> 2) + 4 * hi; }
; #define SWZ(v, pat) __int_as_float(__builtin_amdgcn_ds_swizzle(__float_as_int(v), (pat)))
; __device__ __forceinline__ unsigned f2bf(float f) { unsigned u = __builtin_bit_cast(unsigned, f); return (u + 0x7fffu + ((u >> 16) & 1u)) >> 16; }
; __device__ __forceinline__ KArgP kargs() { KArgP p = (KArgP)__builtin_amdgcn_kernarg_segment_ptr(); asm volatile("" : "+s"(p)); return p; }
; __global__ void __launch_bounds__(NWAVES * 64) fwd_kernel(Args args) {
;     ...
;                         asm volatile("s_waitcnt lgkmcnt(0)" ::: "memory");
;                         const int le_ = ltid() & 63, r32 = le_ & 31, hi = le_ >> 5;
;                         const float* sg = kargs()->in[10]; const unsigned* st = (const unsigned*)(L + att::OFF_O1) + wave * 2048 + (ltid() & 63);
; #pragma unroll
;                         for (int d = 0; d < 4; ++d)
; #pragma unroll
;                             for (int r = 0; r < 16; r += 2) { const unsigned w = st[(d * 8 + (r >> 1)) * 64]; o[d][r] = pg8::bf_lo(w) - lam * o[d][r]; o[d][r + 1] = pg8::bf_hi(w) - lam * o[d][r + 1]; }
;                         float g4[4];
; #pragma unroll
;                         for (int d = 0; d < 4; ++d) g4[d] = sg[d * 32 + r32] * 0.8f;
; #pragma unroll
;                         for (int r = 0; r < 16; ++r) { float s2 = (o[0][r] * o[0][r] + o[1][r] * o[1][r]) + (o[2][r] * o[2][r] + o[3][r] * o[3][r]);
;                             s2 += SWZ(s2, 0x041F); s2 += SWZ(s2, 0x081F); s2 += SWZ(s2, 0x101F); s2 += SWZ(s2, 0x201F); s2 += SWZ(s2, 0x401F);
;                             const float rn = __builtin_amdgcn_rsqf(s2 * (1.0f / 128.0f) + EPS); const int row = qw0 + att::crow(r, hi);
;                             if (row < Lk) { bf16_t* yp = Ys + (size_t)row * DM + head * 128 + r32;
; #pragma unroll
;                                 for (int d = 0; d < 4; ++d) ((__attribute__((address_space(1))) bf16_t*)yp)[d * 32] = (bf16_t)f2bf(o[d][r] * rn * g4[d]); } }
.LBB0_283:
	v_mov_b32_e32 v0, v214
	s_mov_b64 s[0:1], s[68:69]
	s_waitcnt lgkmcnt(0)
	v_mov_b32_e32 v2, v214
	s_load_dwordx2 s[0:1], s[0:1], 0x50
	v_readlane_b32 s3, v254, 39
	v_and_b32_e32 v2, 63, v2
	v_and_b32_e32 v20, 31, v0
	v_lshl_add_u32 v8, v2, 2, s3
	ds_read2st64_b32 v[94:95], v8 offset1:1
	v_lshlrev_b32_e32 v21, 2, v20
	v_readlane_b32 s4, v254, 57
	v_readlane_b32 s5, v254, 58
	s_waitcnt lgkmcnt(0)
	v_lshlrev_b32_e32 v2, 16, v94
	s_waitcnt vmcnt(0)
	v_fma_f32 v78, -v221, v78, v2
	ds_read2st64_b32 v[86:87], v8 offset0:2 offset1:3
	ds_read2st64_b32 v[36:37], v8 offset0:4 offset1:5
	ds_read2st64_b32 v[2:3], v8 offset0:6 offset1:7
	ds_read2st64_b32 v[96:97], v8 offset0:8 offset1:9
	s_waitcnt lgkmcnt(0)
	v_lshlrev_b32_e32 v4, 16, v96
	v_fma_f32 v103, -v221, v80, v4
	ds_read2st64_b32 v[88:89], v8 offset0:10 offset1:11
	ds_read2st64_b32 v[50:51], v8 offset0:12 offset1:13
	ds_read2st64_b32 v[4:5], v8 offset0:14 offset1:15
	ds_read2st64_b32 v[98:99], v8 offset0:16 offset1:17
	s_waitcnt lgkmcnt(0)
	v_lshlrev_b32_e32 v6, 16, v98
	v_fma_f32 v104, -v221, v82, v6
	ds_read2st64_b32 v[90:91], v8 offset0:18 offset1:19
	ds_read2st64_b32 v[52:53], v8 offset0:20 offset1:21
	ds_read2st64_b32 v[6:7], v8 offset0:22 offset1:23
	ds_read2st64_b32 v[100:101], v8 offset0:24 offset1:25
	s_waitcnt lgkmcnt(0)
	v_lshlrev_b32_e32 v9, 16, v100
	v_fma_f32 v105, -v221, v84, v9
	ds_read2st64_b32 v[92:93], v8 offset0:26 offset1:27
	ds_read2st64_b32 v[66:67], v8 offset0:28 offset1:29
	ds_read2st64_b32 v[8:9], v8 offset0:30 offset1:31
	global_load_dword v76, v21, s[0:1]
	v_mul_f32_e32 v77, v105, v105
	v_fmac_f32_e32 v77, v104, v104
	s_waitcnt vmcnt(0)
	v_mul_f32_e32 v80, 0x3f4ccccd, v76
	global_load_dword v76, v21, s[0:1] offset:128
	s_waitcnt vmcnt(0)
	v_mul_f32_e32 v82, 0x3f4ccccd, v76
	global_load_dword v76, v21, s[0:1] offset:256
	s_waitcnt vmcnt(0)
	v_mul_f32_e32 v84, 0x3f4ccccd, v76
	global_load_dword v21, v21, s[0:1] offset:384
	v_readlane_b32 s0, v254, 62
	s_lshl_b32 s0, s0, 1
	s_add_u32 s0, s4, s0
	v_lshrrev_b32_e32 v76, 3, v0
	s_addc_u32 s1, s5, 0
	v_lshlrev_b32_e32 v0, 1, v20
	v_and_or_b32 v76, v76, 4, s29
	v_cmp_gt_i32_e32 vcc, s2, v76
	s_waitcnt vmcnt(0)
	v_mul_f32_e32 v102, 0x3f4ccccd, v21
	v_lshl_add_u64 v[20:21], s[0:1], 0, v[0:1]
	v_mul_f32_e32 v0, v103, v103
	v_fmac_f32_e32 v0, v78, v78
	v_add_f32_e32 v0, v0, v77
	s_nop 1
	v_add_f32_dpp v0, v0, v0 quad_perm:[1,0,3,2] row_mask:0xf bank_mask:0xf
	s_nop 1
	v_add_f32_dpp v0, v0, v0 quad_perm:[2,3,0,1] row_mask:0xf bank_mask:0xf
	s_nop 1
	v_add_f32_dpp v0, v0, v0 row_half_mirror row_mask:0xf bank_mask:0xf
	s_nop 1
	v_add_f32_dpp v0, v0, v0 row_mirror row_mask:0xf bank_mask:0xf
	ds_swizzle_b32 v77, v0 offset:swizzle(SWAP,16)
	s_and_saveexec_b64 s[0:1], vcc
	s_cbranch_execz .LBB0_285
	s_waitcnt lgkmcnt(0)
	v_add_f32_e32 v0, v0, v77
	v_fmamk_f32 v0, v0, 0x3c000000, v215
	v_rsq_f32_e32 v0, v0
	v_ashrrev_i32_e32 v77, 31, v76
	v_lshlrev_b64 v[106:107], 12, v[76:77]
	v_lshl_add_u64 v[106:107], v[20:21], 0, v[106:107]
	v_mul_f32_e32 v77, v0, v78
	v_mul_f32_e32 v77, v80, v77
	v_bfe_u32 v78, v77, 16, 1
	v_add3_u32 v77, v77, v78, s31
	global_store_short_d16_hi v[106:107], v77, off
	v_mul_f32_e32 v77, v0, v103
	v_mul_f32_e32 v77, v82, v77
	v_bfe_u32 v78, v77, 16, 1
	v_add3_u32 v77, v77, v78, s31
	global_store_short_d16_hi v[106:107], v77, off offset:64
	v_mul_f32_e32 v77, v0, v104
	v_mul_f32_e32 v77, v84, v77
	v_bfe_u32 v78, v77, 16, 1
	v_mul_f32_e32 v0, v0, v105
	v_add3_u32 v77, v77, v78, s31
	v_mul_f32_e32 v0, v102, v0
	global_store_short_d16_hi v[106:107], v77, off offset:128
	v_bfe_u32 v77, v0, 16, 1
	v_add3_u32 v0, v0, v77, s31
	global_store_short_d16_hi v[106:107], v0, off offset:192
.LBB0_285:
	s_or_b64 exec, exec, s[0:1]
	v_and_b32_e32 v0, 0xffff0000, v94
	v_fma_f32 v94, -v221, v79, v0
	v_and_b32_e32 v0, 0xffff0000, v96
	v_fma_f32 v81, -v221, v81, v0
	v_and_b32_e32 v0, 0xffff0000, v98
	s_waitcnt lgkmcnt(0)
	v_fma_f32 v77, -v221, v83, v0
	v_and_b32_e32 v0, 0xffff0000, v100
	v_fma_f32 v0, -v221, v85, v0
	v_mul_f32_e32 v78, v81, v81
	v_mul_f32_e32 v79, v0, v0
	v_fmac_f32_e32 v78, v94, v94
	v_fmac_f32_e32 v79, v77, v77
	v_add_f32_e32 v78, v78, v79
	s_nop 1
	v_add_f32_dpp v78, v78, v78 quad_perm:[1,0,3,2] row_mask:0xf bank_mask:0xf
	s_nop 1
	v_add_f32_dpp v78, v78, v78 quad_perm:[2,3,0,1] row_mask:0xf bank_mask:0xf
	s_nop 1
	v_add_f32_dpp v78, v78, v78 row_half_mirror row_mask:0xf bank_mask:0xf
	ds_swizzle_b32 v79, v78 offset:swizzle(SWAP,8)
	s_waitcnt lgkmcnt(0)
	v_add_f32_e32 v79, v78, v79
	ds_swizzle_b32 v83, v79 offset:swizzle(SWAP,16)
	v_or_b32_e32 v78, 1, v76
	v_cmp_gt_i32_e32 vcc, s2, v78
	s_and_saveexec_b64 s[0:1], vcc
	v_readlane_b32 s16, v254, 27
	v_readlane_b32 s26, v254, 55
	v_readlane_b32 s28, v254, 60
	s_mov_b64 s[78:79], 0x80
	v_readlane_b32 s17, v254, 28
	v_readlane_b32 s47, v254, 33
	v_readlane_b32 s27, v254, 56
	v_readlane_b32 s23, v255, 8
	v_readlane_b32 s22, v255, 9
	v_readlane_b32 s29, v254, 61
	v_readlane_b32 s20, v255, 1
	v_readlane_b32 s21, v255, 2
	s_cbranch_execz .LBB0_287
	s_waitcnt lgkmcnt(0)
	v_add_f32_e32 v79, v79, v83
	v_fmamk_f32 v79, v79, 0x3c000000, v215
	v_rsq_f32_e32 v83, v79
	v_ashrrev_i32_e32 v79, 31, v78
	v_lshlrev_b64 v[78:79], 12, v[78:79]
	v_lshl_add_u64 v[78:79], v[20:21], 0, v[78:79]
	v_mul_f32_e32 v85, v83, v94
	v_mul_f32_e32 v85, v80, v85
	v_bfe_u32 v94, v85, 16, 1
	v_mul_f32_e32 v81, v83, v81
	v_add3_u32 v85, v85, v94, s31
	v_mul_f32_e32 v81, v82, v81
	global_store_short_d16_hi v[78:79], v85, off
	v_bfe_u32 v85, v81, 16, 1
	v_mul_f32_e32 v77, v83, v77
	v_add3_u32 v81, v81, v85, s31
	v_mul_f32_e32 v77, v84, v77
	global_store_short_d16_hi v[78:79], v81, off offset:64
	v_bfe_u32 v81, v77, 16, 1
	v_mul_f32_e32 v0, v83, v0
	v_add3_u32 v77, v77, v81, s31
	v_mul_f32_e32 v0, v102, v0
	global_store_short_d16_hi v[78:79], v77, off offset:128
	v_bfe_u32 v77, v0, 16, 1
	v_add3_u32 v0, v0, v77, s31
	global_store_short_d16_hi v[78:79], v0, off offset:192
; __device__ __forceinline__ int crow(int r, int hi) { return (r & 3) + 8 * (r >> 2) + 4 * hi; }
; #define SWZ(v, pat) __int_as_float(__builtin_amdgcn_ds_swizzle(__float_as_int(v), (pat)))
; __device__ __forceinline__ unsigned f2bf(float f) { unsigned u = __builtin_bit_cast(unsigned, f); return (u + 0x7fffu + ((u >> 16) & 1u)) >> 16; }
; __global__ void __launch_bounds__(NWAVES * 64) fwd_kernel(Args args) {
;     ...
;                         for (int r = 0; r < 16; ++r) { float s2 = (o[0][r] * o[0][r] + o[1][r] * o[1][r]) + (o[2][r] * o[2][r] + o[3][r] * o[3][r]);
;                             s2 += SWZ(s2, 0x041F); s2 += SWZ(s2, 0x081F); s2 += SWZ(s2, 0x101F); s2 += SWZ(s2, 0x201F); s2 += SWZ(s2, 0x401F);
;                             const float rn = __builtin_amdgcn_rsqf(s2 * (1.0f / 128.0f) + EPS); const int row = qw0 + att::crow(r, hi);
;                             if (row < Lk) { bf16_t* yp = Ys + (size_t)row * DM + head * 128 + r32;
; #pragma unroll
;                                 for (int d = 0; d < 4; ++d) ((__attribute__((address_space(1))) bf16_t*)yp)[d * 32] = (bf16_t)f2bf(o[d][r] * rn * g4[d]); } }
.LBB0_287:
	s_or_b64 exec, exec, s[0:1]
	v_lshlrev_b32_e32 v0, 16, v95
	v_fma_f32 v77, -v221, v68, v0
	v_lshlrev_b32_e32 v0, 16, v97
	v_fma_f32 v70, -v221, v70, v0
	v_lshlrev_b32_e32 v0, 16, v99
	v_fma_f32 v68, -v221, v72, v0
	v_lshlrev_b32_e32 v0, 16, v101
	v_fma_f32 v0, -v221, v74, v0
	v_mul_f32_e32 v72, v70, v70
	v_mul_f32_e32 v74, v0, v0
	v_fmac_f32_e32 v72, v77, v77
	v_fmac_f32_e32 v74, v68, v68
	v_add_f32_e32 v72, v72, v74
	ds_swizzle_b32 v74, v72 offset:swizzle(SWAP,1)
	v_or_b32_e32 v78, 2, v76
	v_cmp_gt_i32_e32 vcc, s2, v78
	s_waitcnt lgkmcnt(0)
	v_add_f32_e32 v72, v72, v74
	s_nop 1
	v_add_f32_dpp v72, v72, v72 quad_perm:[2,3,0,1] row_mask:0xf bank_mask:0xf
	s_nop 1
	v_add_f32_dpp v72, v72, v72 row_half_mirror row_mask:0xf bank_mask:0xf
	s_nop 1
	v_add_f32_dpp v72, v72, v72 row_mirror row_mask:0xf bank_mask:0xf
	ds_swizzle_b32 v74, v72 offset:swizzle(SWAP,16)
	s_and_saveexec_b64 s[0:1], vcc
	s_cbranch_execz .LBB0_289
	s_waitcnt lgkmcnt(0)
	v_add_f32_e32 v72, v72, v74
	v_fmamk_f32 v72, v72, 0x3c000000, v215
	v_rsq_f32_e32 v72, v72
	v_ashrrev_i32_e32 v79, 31, v78
	v_lshlrev_b64 v[78:79], 12, v[78:79]
	v_lshl_add_u64 v[78:79], v[20:21], 0, v[78:79]
	v_mul_f32_e32 v74, v72, v77
	v_mul_f32_e32 v74, v80, v74
	v_bfe_u32 v77, v74, 16, 1
	v_mul_f32_e32 v70, v72, v70
	v_add3_u32 v74, v74, v77, s31
	v_mul_f32_e32 v70, v82, v70
	global_store_short_d16_hi v[78:79], v74, off
	v_bfe_u32 v74, v70, 16, 1
	v_mul_f32_e32 v68, v72, v68
	v_add3_u32 v70, v70, v74, s31
	v_mul_f32_e32 v68, v84, v68
	global_store_short_d16_hi v[78:79], v70, off offset:64
	v_bfe_u32 v70, v68, 16, 1
	v_mul_f32_e32 v0, v72, v0
	v_add3_u32 v68, v68, v70, s31
	v_mul_f32_e32 v0, v102, v0
	global_store_short_d16_hi v[78:79], v68, off offset:128
	v_bfe_u32 v68, v0, 16, 1
	v_add3_u32 v0, v0, v68, s31
	global_store_short_d16_hi v[78:79], v0, off offset:192
.LBB0_289:
	s_or_b64 exec, exec, s[0:1]
	v_and_b32_e32 v0, 0xffff0000, v95
	v_fma_f32 v72, -v221, v69, v0
	v_and_b32_e32 v0, 0xffff0000, v97
	v_fma_f32 v71, -v221, v71, v0
	v_and_b32_e32 v0, 0xffff0000, v99
	v_fma_f32 v70, -v221, v73, v0
	v_and_b32_e32 v0, 0xffff0000, v101
	v_fma_f32 v0, -v221, v75, v0
	v_mul_f32_e32 v68, v71, v71
	v_mul_f32_e32 v69, v0, v0
	v_fmac_f32_e32 v68, v72, v72
	v_fmac_f32_e32 v69, v70, v70
	v_add_f32_e32 v68, v68, v69
	s_nop 1
	v_add_f32_dpp v68, v68, v68 quad_perm:[1,0,3,2] row_mask:0xf bank_mask:0xf
	s_nop 1
	v_add_f32_dpp v68, v68, v68 quad_perm:[2,3,0,1] row_mask:0xf bank_mask:0xf
	s_nop 1
	v_add_f32_dpp v68, v68, v68 row_half_mirror row_mask:0xf bank_mask:0xf
	ds_swizzle_b32 v69, v68 offset:swizzle(SWAP,8)
	s_waitcnt lgkmcnt(0)
	v_add_f32_e32 v69, v68, v69
	ds_swizzle_b32 v73, v69 offset:swizzle(SWAP,16)
	v_or_b32_e32 v68, 3, v76
	v_cmp_gt_i32_e32 vcc, s2, v68
	s_and_saveexec_b64 s[0:1], vcc
	s_cbranch_execz .LBB0_291
	s_waitcnt lgkmcnt(0)
	v_add_f32_e32 v69, v69, v73
	v_fmamk_f32 v69, v69, 0x3c000000, v215
	v_rsq_f32_e32 v73, v69
	v_ashrrev_i32_e32 v69, 31, v68
	v_lshlrev_b64 v[68:69], 12, v[68:69]
	v_lshl_add_u64 v[68:69], v[20:21], 0, v[68:69]
	v_mul_f32_e32 v72, v73, v72
	v_mul_f32_e32 v72, v80, v72
	v_bfe_u32 v74, v72, 16, 1
	v_mul_f32_e32 v71, v73, v71
	v_add3_u32 v72, v72, v74, s31
	v_mul_f32_e32 v71, v82, v71
	global_store_short_d16_hi v[68:69], v72, off
	v_bfe_u32 v72, v71, 16, 1
	v_mul_f32_e32 v70, v73, v70
	v_add3_u32 v71, v71, v72, s31
	v_mul_f32_e32 v70, v84, v70
	global_store_short_d16_hi v[68:69], v71, off offset:64
	v_bfe_u32 v71, v70, 16, 1
	v_mul_f32_e32 v0, v73, v0
	v_add3_u32 v70, v70, v71, s31
	v_mul_f32_e32 v0, v102, v0
	global_store_short_d16_hi v[68:69], v70, off offset:128
	v_bfe_u32 v70, v0, 16, 1
	v_add3_u32 v0, v0, v70, s31
	global_store_short_d16_hi v[68:69], v0, off offset:192
.LBB0_291:
	s_or_b64 exec, exec, s[0:1]
	v_lshlrev_b32_e32 v0, 16, v86
	v_fma_f32 v54, -v221, v54, v0
	v_lshlrev_b32_e32 v0, 16, v88
	v_fma_f32 v38, -v221, v38, v0
	v_lshlrev_b32_e32 v0, 16, v90
	v_fma_f32 v22, -v221, v22, v0
	v_lshlrev_b32_e32 v0, 16, v92
	v_fma_f32 v0, -v221, v34, v0
	v_mul_f32_e32 v34, v38, v38
	v_mul_f32_e32 v68, v0, v0
	v_fmac_f32_e32 v34, v54, v54
	v_fmac_f32_e32 v68, v22, v22
	v_add_f32_e32 v34, v34, v68
	s_nop 1
	v_add_f32_dpp v34, v34, v34 quad_perm:[1,0,3,2] row_mask:0xf bank_mask:0xf
	s_nop 1
	v_add_f32_dpp v34, v34, v34 quad_perm:[2,3,0,1] row_mask:0xf bank_mask:0xf
	s_nop 1
	v_add_f32_dpp v34, v34, v34 row_half_mirror row_mask:0xf bank_mask:0xf
	ds_swizzle_b32 v68, v34 offset:swizzle(SWAP,8)
	s_waitcnt lgkmcnt(0)
	v_add_f32_e32 v34, v34, v68
	ds_swizzle_b32 v69, v34 offset:swizzle(SWAP,16)
	v_or_b32_e32 v68, 8, v76
	v_cmp_gt_i32_e32 vcc, s2, v68
	s_and_saveexec_b64 s[0:1], vcc
	s_cbranch_execz .LBB0_293
	s_waitcnt lgkmcnt(0)
	v_add_f32_e32 v34, v34, v69
	v_fmamk_f32 v34, v34, 0x3c000000, v215
	v_rsq_f32_e32 v34, v34
	v_ashrrev_i32_e32 v69, 31, v68
	v_lshlrev_b64 v[68:69], 12, v[68:69]
	v_lshl_add_u64 v[68:69], v[20:21], 0, v[68:69]
	v_mul_f32_e32 v54, v34, v54
	v_mul_f32_e32 v54, v80, v54
	v_bfe_u32 v70, v54, 16, 1
	v_mul_f32_e32 v38, v34, v38
	v_add3_u32 v54, v54, v70, s31
	v_mul_f32_e32 v38, v82, v38
	global_store_short_d16_hi v[68:69], v54, off
	v_bfe_u32 v54, v38, 16, 1
	v_mul_f32_e32 v22, v34, v22
	v_add3_u32 v38, v38, v54, s31
	v_mul_f32_e32 v22, v84, v22
	global_store_short_d16_hi v[68:69], v38, off offset:64
	v_bfe_u32 v38, v22, 16, 1
	v_mul_f32_e32 v0, v34, v0
	v_add3_u32 v22, v22, v38, s31
	v_mul_f32_e32 v0, v102, v0
	global_store_short_d16_hi v[68:69], v22, off offset:128
	v_bfe_u32 v22, v0, 16, 1
	v_add3_u32 v0, v0, v22, s31
	global_store_short_d16_hi v[68:69], v0, off offset:192
; __device__ __forceinline__ int crow(int r, int hi) { return (r & 3) + 8 * (r >> 2) + 4 * hi; }
; #define SWZ(v, pat) __int_as_float(__builtin_amdgcn_ds_swizzle(__float_as_int(v), (pat)))
; __device__ __forceinline__ unsigned f2bf(float f) { unsigned u = __builtin_bit_cast(unsigned, f); return (u + 0x7fffu + ((u >> 16) & 1u)) >> 16; }
; __global__ void __launch_bounds__(NWAVES * 64) fwd_kernel(Args args) {
;     ...
;                         for (int r = 0; r < 16; ++r) { float s2 = (o[0][r] * o[0][r] + o[1][r] * o[1][r]) + (o[2][r] * o[2][r] + o[3][r] * o[3][r]);
;                             s2 += SWZ(s2, 0x041F); s2 += SWZ(s2, 0x081F); s2 += SWZ(s2, 0x101F); s2 += SWZ(s2, 0x201F); s2 += SWZ(s2, 0x401F);
;                             const float rn = __builtin_amdgcn_rsqf(s2 * (1.0f / 128.0f) + EPS); const int row = qw0 + att::crow(r, hi);
;                             if (row < Lk) { bf16_t* yp = Ys + (size_t)row * DM + head * 128 + r32;
; #pragma unroll
;                                 for (int d = 0; d < 4; ++d) ((__attribute__((address_space(1))) bf16_t*)yp)[d * 32] = (bf16_t)f2bf(o[d][r] * rn * g4[d]); } }
.LBB0_293:
	s_or_b64 exec, exec, s[0:1]
	v_and_b32_e32 v0, 0xffff0000, v86
	v_fma_f32 v54, -v221, v55, v0
	v_and_b32_e32 v0, 0xffff0000, v88
	v_fma_f32 v38, -v221, v39, v0
	v_and_b32_e32 v0, 0xffff0000, v90
	v_fma_f32 v34, -v221, v23, v0
	v_and_b32_e32 v0, 0xffff0000, v92
	v_fma_f32 v0, -v221, v35, v0
	v_mul_f32_e32 v22, v38, v38
	v_mul_f32_e32 v23, v0, v0
	v_fmac_f32_e32 v22, v54, v54
	v_fmac_f32_e32 v23, v34, v34
	v_add_f32_e32 v22, v22, v23
	s_nop 1
	v_add_f32_dpp v22, v22, v22 quad_perm:[1,0,3,2] row_mask:0xf bank_mask:0xf
	s_nop 1
	v_add_f32_dpp v22, v22, v22 quad_perm:[2,3,0,1] row_mask:0xf bank_mask:0xf
	s_nop 1
	v_add_f32_dpp v22, v22, v22 row_half_mirror row_mask:0xf bank_mask:0xf
	ds_swizzle_b32 v23, v22 offset:swizzle(SWAP,8)
	s_waitcnt lgkmcnt(0)
	v_add_f32_e32 v23, v22, v23
	ds_swizzle_b32 v35, v23 offset:swizzle(SWAP,16)
	v_or_b32_e32 v22, 9, v76
	v_cmp_gt_i32_e32 vcc, s2, v22
	s_and_saveexec_b64 s[0:1], vcc
	s_cbranch_execz .LBB0_295
	s_waitcnt lgkmcnt(0)
	v_add_f32_e32 v23, v23, v35
	v_fmamk_f32 v23, v23, 0x3c000000, v215
	v_rsq_f32_e32 v35, v23
	v_ashrrev_i32_e32 v23, 31, v22
	v_lshlrev_b64 v[22:23], 12, v[22:23]
	v_lshl_add_u64 v[22:23], v[20:21], 0, v[22:23]
	v_mul_f32_e32 v39, v35, v54
	v_mul_f32_e32 v39, v80, v39
	v_bfe_u32 v54, v39, 16, 1
	v_mul_f32_e32 v38, v35, v38
	v_add3_u32 v39, v39, v54, s31
	v_mul_f32_e32 v38, v82, v38
	global_store_short_d16_hi v[22:23], v39, off
	v_bfe_u32 v39, v38, 16, 1
	v_mul_f32_e32 v34, v35, v34
	v_add3_u32 v38, v38, v39, s31
	v_mul_f32_e32 v34, v84, v34
	global_store_short_d16_hi v[22:23], v38, off offset:64
	v_bfe_u32 v38, v34, 16, 1
	v_mul_f32_e32 v0, v35, v0
	v_add3_u32 v34, v34, v38, s31
	v_mul_f32_e32 v0, v102, v0
	global_store_short_d16_hi v[22:23], v34, off offset:128
	v_bfe_u32 v34, v0, 16, 1
	v_add3_u32 v0, v0, v34, s31
	global_store_short_d16_hi v[22:23], v0, off offset:192
.LBB0_295:
	s_or_b64 exec, exec, s[0:1]
	v_lshlrev_b32_e32 v0, 16, v87
	s_waitcnt lgkmcnt(0)
	v_fma_f32 v35, -v221, v56, v0
	v_lshlrev_b32_e32 v0, 16, v89
	v_fma_f32 v34, -v221, v40, v0
	v_lshlrev_b32_e32 v0, 16, v91
	v_fma_f32 v24, -v221, v24, v0
	v_lshlrev_b32_e32 v0, 16, v93
	v_fma_f32 v0, -v221, v18, v0
	v_mul_f32_e32 v18, v34, v34
	v_mul_f32_e32 v22, v0, v0
	v_fmac_f32_e32 v18, v35, v35
	v_fmac_f32_e32 v22, v24, v24
	v_add_f32_e32 v18, v18, v22
	s_nop 1
	v_add_f32_dpp v18, v18, v18 quad_perm:[1,0,3,2] row_mask:0xf bank_mask:0xf
	s_nop 1
	v_add_f32_dpp v18, v18, v18 quad_perm:[2,3,0,1] row_mask:0xf bank_mask:0xf
	s_nop 1
	v_add_f32_dpp v18, v18, v18 row_half_mirror row_mask:0xf bank_mask:0xf
	ds_swizzle_b32 v22, v18 offset:swizzle(SWAP,8)
	s_waitcnt lgkmcnt(0)
	v_add_f32_e32 v18, v18, v22
	ds_swizzle_b32 v23, v18 offset:swizzle(SWAP,16)
	v_or_b32_e32 v22, 10, v76
	v_cmp_gt_i32_e32 vcc, s2, v22
	s_and_saveexec_b64 s[0:1], vcc
	s_cbranch_execz .LBB0_297
	s_waitcnt lgkmcnt(0)
	v_add_f32_e32 v18, v18, v23
	v_fmamk_f32 v18, v18, 0x3c000000, v215
	v_rsq_f32_e32 v18, v18
	v_ashrrev_i32_e32 v23, 31, v22
	v_lshlrev_b64 v[22:23], 12, v[22:23]
	v_lshl_add_u64 v[22:23], v[20:21], 0, v[22:23]
	v_mul_f32_e32 v35, v18, v35
	v_mul_f32_e32 v35, v80, v35
	v_bfe_u32 v38, v35, 16, 1
	v_mul_f32_e32 v34, v18, v34
	v_add3_u32 v35, v35, v38, s31
	v_mul_f32_e32 v34, v82, v34
	global_store_short_d16_hi v[22:23], v35, off
	v_bfe_u32 v35, v34, 16, 1
	v_mul_f32_e32 v24, v18, v24
	v_mul_f32_e32 v0, v18, v0
	v_add3_u32 v34, v34, v35, s31
	v_mul_f32_e32 v24, v84, v24
	v_mul_f32_e32 v0, v102, v0
	global_store_short_d16_hi v[22:23], v34, off offset:64
	v_bfe_u32 v34, v24, 16, 1
	v_bfe_u32 v18, v0, 16, 1
	v_add3_u32 v24, v24, v34, s31
	v_add3_u32 v0, v0, v18, s31
	global_store_short_d16_hi v[22:23], v24, off offset:128
	global_store_short_d16_hi v[22:23], v0, off offset:192
.LBB0_297:
	s_or_b64 exec, exec, s[0:1]
	v_and_b32_e32 v0, 0xffff0000, v87
	v_fma_f32 v24, -v221, v57, v0
	v_and_b32_e32 v0, 0xffff0000, v89
	s_waitcnt lgkmcnt(0)
	v_fma_f32 v23, -v221, v41, v0
	v_and_b32_e32 v0, 0xffff0000, v91
	v_fma_f32 v22, -v221, v25, v0
	v_and_b32_e32 v0, 0xffff0000, v93
	v_fma_f32 v0, -v221, v19, v0
	v_mul_f32_e32 v18, v23, v23
	v_mul_f32_e32 v19, v0, v0
	v_fmac_f32_e32 v18, v24, v24
	v_fmac_f32_e32 v19, v22, v22
	v_add_f32_e32 v18, v18, v19
	s_nop 1
	v_add_f32_dpp v18, v18, v18 quad_perm:[1,0,3,2] row_mask:0xf bank_mask:0xf
	s_nop 1
	v_add_f32_dpp v18, v18, v18 quad_perm:[2,3,0,1] row_mask:0xf bank_mask:0xf
	s_nop 1
	v_add_f32_dpp v18, v18, v18 row_half_mirror row_mask:0xf bank_mask:0xf
	ds_swizzle_b32 v19, v18 offset:swizzle(SWAP,8)
	s_waitcnt lgkmcnt(0)
	v_add_f32_e32 v19, v18, v19
	ds_swizzle_b32 v25, v19 offset:swizzle(SWAP,16)
	v_or_b32_e32 v18, 11, v76
	v_cmp_gt_i32_e32 vcc, s2, v18
	s_and_saveexec_b64 s[0:1], vcc
	s_cbranch_execz .LBB0_299
	s_waitcnt lgkmcnt(0)
	v_add_f32_e32 v19, v19, v25
	v_fmamk_f32 v19, v19, 0x3c000000, v215
	v_rsq_f32_e32 v25, v19
	v_ashrrev_i32_e32 v19, 31, v18
	v_lshlrev_b64 v[18:19], 12, v[18:19]
	v_lshl_add_u64 v[18:19], v[20:21], 0, v[18:19]
	v_mul_f32_e32 v24, v25, v24
	v_mul_f32_e32 v24, v80, v24
	v_bfe_u32 v34, v24, 16, 1
	v_mul_f32_e32 v23, v25, v23
	v_add3_u32 v24, v24, v34, s31
	v_mul_f32_e32 v23, v82, v23
	global_store_short_d16_hi v[18:19], v24, off
	v_bfe_u32 v24, v23, 16, 1
	v_mul_f32_e32 v22, v25, v22
	v_add3_u32 v23, v23, v24, s31
	v_mul_f32_e32 v22, v84, v22
	global_store_short_d16_hi v[18:19], v23, off offset:64
	v_bfe_u32 v23, v22, 16, 1
	v_mul_f32_e32 v0, v25, v0
	v_add3_u32 v22, v22, v23, s31
	v_mul_f32_e32 v0, v102, v0
	global_store_short_d16_hi v[18:19], v22, off offset:128
	v_bfe_u32 v22, v0, 16, 1
	v_add3_u32 v0, v0, v22, s31
	global_store_short_d16_hi v[18:19], v0, off offset:192
; __device__ __forceinline__ int crow(int r, int hi) { return (r & 3) + 8 * (r >> 2) + 4 * hi; }
; #define SWZ(v, pat) __int_as_float(__builtin_amdgcn_ds_swizzle(__float_as_int(v), (pat)))
; __device__ __forceinline__ unsigned f2bf(float f) { unsigned u = __builtin_bit_cast(unsigned, f); return (u + 0x7fffu + ((u >> 16) & 1u)) >> 16; }
; __global__ void __launch_bounds__(NWAVES * 64) fwd_kernel(Args args) {
;     ...
;                         for (int r = 0; r < 16; ++r) { float s2 = (o[0][r] * o[0][r] + o[1][r] * o[1][r]) + (o[2][r] * o[2][r] + o[3][r] * o[3][r]);
;                             s2 += SWZ(s2, 0x041F); s2 += SWZ(s2, 0x081F); s2 += SWZ(s2, 0x101F); s2 += SWZ(s2, 0x201F); s2 += SWZ(s2, 0x401F);
;                             const float rn = __builtin_amdgcn_rsqf(s2 * (1.0f / 128.0f) + EPS); const int row = qw0 + att::crow(r, hi);
;                             if (row < Lk) { bf16_t* yp = Ys + (size_t)row * DM + head * 128 + r32;
; #pragma unroll
;                                 for (int d = 0; d < 4; ++d) ((__attribute__((address_space(1))) bf16_t*)yp)[d * 32] = (bf16_t)f2bf(o[d][r] * rn * g4[d]); } }
.LBB0_299:
	s_or_b64 exec, exec, s[0:1]
	v_lshlrev_b32_e32 v0, 16, v36
	v_fma_f32 v24, -v221, v58, v0
	v_lshlrev_b32_e32 v0, 16, v50
	v_fma_f32 v23, -v221, v42, v0
	v_lshlrev_b32_e32 v0, 16, v52
	v_fma_f32 v22, -v221, v26, v0
	v_lshlrev_b32_e32 v0, 16, v66
	v_fma_f32 v0, -v221, v10, v0
	v_mul_f32_e32 v10, v23, v23
	v_mul_f32_e32 v18, v0, v0
	v_fmac_f32_e32 v10, v24, v24
	v_fmac_f32_e32 v18, v22, v22
	v_add_f32_e32 v10, v10, v18
	s_nop 1
	v_add_f32_dpp v10, v10, v10 quad_perm:[1,0,3,2] row_mask:0xf bank_mask:0xf
	s_nop 1
	v_add_f32_dpp v10, v10, v10 quad_perm:[2,3,0,1] row_mask:0xf bank_mask:0xf
	s_nop 1
	v_add_f32_dpp v10, v10, v10 row_half_mirror row_mask:0xf bank_mask:0xf
	ds_swizzle_b32 v18, v10 offset:swizzle(SWAP,8)
	s_waitcnt lgkmcnt(0)
	v_add_f32_e32 v10, v10, v18
	ds_swizzle_b32 v19, v10 offset:swizzle(SWAP,16)
	v_or_b32_e32 v18, 16, v76
	v_cmp_gt_i32_e32 vcc, s2, v18
	s_and_saveexec_b64 s[0:1], vcc
	s_cbranch_execz .LBB0_301
	s_waitcnt lgkmcnt(0)
	v_add_f32_e32 v10, v10, v19
	v_fmamk_f32 v10, v10, 0x3c000000, v215
	v_rsq_f32_e32 v10, v10
	v_ashrrev_i32_e32 v19, 31, v18
	v_lshlrev_b64 v[18:19], 12, v[18:19]
	v_lshl_add_u64 v[18:19], v[20:21], 0, v[18:19]
	v_mul_f32_e32 v24, v10, v24
	v_mul_f32_e32 v24, v80, v24
	v_bfe_u32 v25, v24, 16, 1
	v_mul_f32_e32 v23, v10, v23
	v_add3_u32 v24, v24, v25, s31
	v_mul_f32_e32 v23, v82, v23
	global_store_short_d16_hi v[18:19], v24, off
	v_bfe_u32 v24, v23, 16, 1
	v_mul_f32_e32 v22, v10, v22
	v_mul_f32_e32 v0, v10, v0
	v_add3_u32 v23, v23, v24, s31
	v_mul_f32_e32 v22, v84, v22
	v_mul_f32_e32 v0, v102, v0
	global_store_short_d16_hi v[18:19], v23, off offset:64
	v_bfe_u32 v23, v22, 16, 1
	v_bfe_u32 v10, v0, 16, 1
	v_add3_u32 v22, v22, v23, s31
	v_add3_u32 v0, v0, v10, s31
	global_store_short_d16_hi v[18:19], v22, off offset:128
	global_store_short_d16_hi v[18:19], v0, off offset:192
.LBB0_301:
	s_or_b64 exec, exec, s[0:1]
	v_and_b32_e32 v0, 0xffff0000, v36
	v_fma_f32 v22, -v221, v59, v0
	v_and_b32_e32 v0, 0xffff0000, v50
	s_waitcnt lgkmcnt(0)
	v_fma_f32 v19, -v221, v43, v0
	v_and_b32_e32 v0, 0xffff0000, v52
	v_fma_f32 v18, -v221, v27, v0
	v_and_b32_e32 v0, 0xffff0000, v66
	v_fma_f32 v0, -v221, v11, v0
	v_mul_f32_e32 v10, v19, v19
	v_mul_f32_e32 v11, v0, v0
	v_fmac_f32_e32 v10, v22, v22
	v_fmac_f32_e32 v11, v18, v18
	v_add_f32_e32 v10, v10, v11
	s_nop 1
	v_add_f32_dpp v10, v10, v10 quad_perm:[1,0,3,2] row_mask:0xf bank_mask:0xf
	s_nop 1
	v_add_f32_dpp v10, v10, v10 quad_perm:[2,3,0,1] row_mask:0xf bank_mask:0xf
	s_nop 1
	v_add_f32_dpp v10, v10, v10 row_half_mirror row_mask:0xf bank_mask:0xf
	ds_swizzle_b32 v11, v10 offset:swizzle(SWAP,8)
	s_waitcnt lgkmcnt(0)
	v_add_f32_e32 v11, v10, v11
	ds_swizzle_b32 v23, v11 offset:swizzle(SWAP,16)
	v_or_b32_e32 v10, 17, v76
	v_cmp_gt_i32_e32 vcc, s2, v10
	s_and_saveexec_b64 s[0:1], vcc
	s_cbranch_execz .LBB0_303
	s_waitcnt lgkmcnt(0)
	v_add_f32_e32 v11, v11, v23
	v_fmamk_f32 v11, v11, 0x3c000000, v215
	v_rsq_f32_e32 v23, v11
	v_ashrrev_i32_e32 v11, 31, v10
	v_lshlrev_b64 v[10:11], 12, v[10:11]
	v_lshl_add_u64 v[10:11], v[20:21], 0, v[10:11]
	v_mul_f32_e32 v22, v23, v22
	v_mul_f32_e32 v22, v80, v22
	v_bfe_u32 v24, v22, 16, 1
	v_mul_f32_e32 v19, v23, v19
	v_add3_u32 v22, v22, v24, s31
	v_mul_f32_e32 v19, v82, v19
	global_store_short_d16_hi v[10:11], v22, off
	v_bfe_u32 v22, v19, 16, 1
	v_mul_f32_e32 v18, v23, v18
	v_add3_u32 v19, v19, v22, s31
	v_mul_f32_e32 v18, v84, v18
	global_store_short_d16_hi v[10:11], v19, off offset:64
	v_bfe_u32 v19, v18, 16, 1
	v_mul_f32_e32 v0, v23, v0
	v_add3_u32 v18, v18, v19, s31
	v_mul_f32_e32 v0, v102, v0
	global_store_short_d16_hi v[10:11], v18, off offset:128
	v_bfe_u32 v18, v0, 16, 1
	v_add3_u32 v0, v0, v18, s31
	global_store_short_d16_hi v[10:11], v0, off offset:192
.LBB0_303:
	s_or_b64 exec, exec, s[0:1]
	v_lshlrev_b32_e32 v0, 16, v37
	v_fma_f32 v22, -v221, v60, v0
	v_lshlrev_b32_e32 v0, 16, v51
	v_fma_f32 v19, -v221, v44, v0
	v_lshlrev_b32_e32 v0, 16, v53
	v_fma_f32 v18, -v221, v28, v0
	v_lshlrev_b32_e32 v0, 16, v67
	v_fma_f32 v0, -v221, v12, v0
	v_mul_f32_e32 v10, v19, v19
	v_mul_f32_e32 v11, v0, v0
	v_fmac_f32_e32 v10, v22, v22
	v_fmac_f32_e32 v11, v18, v18
	v_add_f32_e32 v10, v10, v11
	s_nop 1
	v_add_f32_dpp v10, v10, v10 quad_perm:[1,0,3,2] row_mask:0xf bank_mask:0xf
	s_nop 1
	v_add_f32_dpp v10, v10, v10 quad_perm:[2,3,0,1] row_mask:0xf bank_mask:0xf
	s_nop 1
	v_add_f32_dpp v10, v10, v10 row_half_mirror row_mask:0xf bank_mask:0xf
	ds_swizzle_b32 v11, v10 offset:swizzle(SWAP,8)
	s_waitcnt lgkmcnt(0)
	v_add_f32_e32 v11, v10, v11
	ds_swizzle_b32 v12, v11 offset:swizzle(SWAP,16)
	v_or_b32_e32 v10, 18, v76
	v_cmp_gt_i32_e32 vcc, s2, v10
	s_and_saveexec_b64 s[0:1], vcc
	s_cbranch_execz .LBB0_305
	s_waitcnt lgkmcnt(0)
	v_add_f32_e32 v11, v11, v12
	v_fmamk_f32 v11, v11, 0x3c000000, v215
	v_rsq_f32_e32 v12, v11
	v_ashrrev_i32_e32 v11, 31, v10
	v_lshlrev_b64 v[10:11], 12, v[10:11]
	v_lshl_add_u64 v[10:11], v[20:21], 0, v[10:11]
	v_mul_f32_e32 v22, v12, v22
	v_mul_f32_e32 v22, v80, v22
	v_bfe_u32 v23, v22, 16, 1
	v_mul_f32_e32 v19, v12, v19
	v_add3_u32 v22, v22, v23, s31
	v_mul_f32_e32 v19, v82, v19
	global_store_short_d16_hi v[10:11], v22, off
	v_bfe_u32 v22, v19, 16, 1
	v_mul_f32_e32 v18, v12, v18
	v_mul_f32_e32 v0, v12, v0
	v_add3_u32 v19, v19, v22, s31
	v_mul_f32_e32 v18, v84, v18
	v_mul_f32_e32 v0, v102, v0
	global_store_short_d16_hi v[10:11], v19, off offset:64
	v_bfe_u32 v19, v18, 16, 1
	v_bfe_u32 v12, v0, 16, 1
	v_add3_u32 v18, v18, v19, s31
	v_add3_u32 v0, v0, v12, s31
	global_store_short_d16_hi v[10:11], v18, off offset:128
	global_store_short_d16_hi v[10:11], v0, off offset:192
; __device__ __forceinline__ int crow(int r, int hi) { return (r & 3) + 8 * (r >> 2) + 4 * hi; }
; #define SWZ(v, pat) __int_as_float(__builtin_amdgcn_ds_swizzle(__float_as_int(v), (pat)))
; __device__ __forceinline__ unsigned f2bf(float f) { unsigned u = __builtin_bit_cast(unsigned, f); return (u + 0x7fffu + ((u >> 16) & 1u)) >> 16; }
; __global__ void __launch_bounds__(NWAVES * 64) fwd_kernel(Args args) {
;     ...
;                         for (int r = 0; r < 16; ++r) { float s2 = (o[0][r] * o[0][r] + o[1][r] * o[1][r]) + (o[2][r] * o[2][r] + o[3][r] * o[3][r]);
;                             s2 += SWZ(s2, 0x041F); s2 += SWZ(s2, 0x081F); s2 += SWZ(s2, 0x101F); s2 += SWZ(s2, 0x201F); s2 += SWZ(s2, 0x401F);
;                             const float rn = __builtin_amdgcn_rsqf(s2 * (1.0f / 128.0f) + EPS); const int row = qw0 + att::crow(r, hi);
;                             if (row < Lk) { bf16_t* yp = Ys + (size_t)row * DM + head * 128 + r32;
; #pragma unroll
;                                 for (int d = 0; d < 4; ++d) ((__attribute__((address_space(1))) bf16_t*)yp)[d * 32] = (bf16_t)f2bf(o[d][r] * rn * g4[d]); } }
.LBB0_305:
	s_or_b64 exec, exec, s[0:1]
	v_and_b32_e32 v0, 0xffff0000, v37
	v_fma_f32 v19, -v221, v61, v0
	v_and_b32_e32 v0, 0xffff0000, v51
	v_fma_f32 v18, -v221, v45, v0
	v_and_b32_e32 v0, 0xffff0000, v53
	s_waitcnt lgkmcnt(0)
	v_fma_f32 v12, -v221, v29, v0
	v_and_b32_e32 v0, 0xffff0000, v67
	v_fma_f32 v0, -v221, v13, v0
	v_mul_f32_e32 v10, v18, v18
	v_mul_f32_e32 v11, v0, v0
	v_fmac_f32_e32 v10, v19, v19
	v_fmac_f32_e32 v11, v12, v12
	v_add_f32_e32 v10, v10, v11
	s_nop 1
	v_add_f32_dpp v10, v10, v10 quad_perm:[1,0,3,2] row_mask:0xf bank_mask:0xf
	s_nop 1
	v_add_f32_dpp v10, v10, v10 quad_perm:[2,3,0,1] row_mask:0xf bank_mask:0xf
	s_nop 1
	v_add_f32_dpp v10, v10, v10 row_half_mirror row_mask:0xf bank_mask:0xf
	ds_swizzle_b32 v11, v10 offset:swizzle(SWAP,8)
	s_waitcnt lgkmcnt(0)
	v_add_f32_e32 v11, v10, v11
	ds_swizzle_b32 v13, v11 offset:swizzle(SWAP,16)
	v_or_b32_e32 v10, 19, v76
	v_cmp_gt_i32_e32 vcc, s2, v10
	s_and_saveexec_b64 s[0:1], vcc
	s_cbranch_execz .LBB0_307
	s_waitcnt lgkmcnt(0)
	v_add_f32_e32 v11, v11, v13
	v_fmamk_f32 v11, v11, 0x3c000000, v215
	v_rsq_f32_e32 v13, v11
	v_ashrrev_i32_e32 v11, 31, v10
	v_lshlrev_b64 v[10:11], 12, v[10:11]
	v_lshl_add_u64 v[10:11], v[20:21], 0, v[10:11]
	v_mul_f32_e32 v19, v13, v19
	v_mul_f32_e32 v19, v80, v19
	v_bfe_u32 v22, v19, 16, 1
	v_mul_f32_e32 v18, v13, v18
	v_add3_u32 v19, v19, v22, s31
	v_mul_f32_e32 v18, v82, v18
	global_store_short_d16_hi v[10:11], v19, off
	v_bfe_u32 v19, v18, 16, 1
	v_mul_f32_e32 v12, v13, v12
	v_add3_u32 v18, v18, v19, s31
	v_mul_f32_e32 v12, v84, v12
	global_store_short_d16_hi v[10:11], v18, off offset:64
	v_bfe_u32 v18, v12, 16, 1
	v_mul_f32_e32 v0, v13, v0
	v_add3_u32 v12, v12, v18, s31
	v_mul_f32_e32 v0, v102, v0
	global_store_short_d16_hi v[10:11], v12, off offset:128
	v_bfe_u32 v12, v0, 16, 1
	v_add3_u32 v0, v0, v12, s31
	global_store_short_d16_hi v[10:11], v0, off offset:192
.LBB0_307:
	s_or_b64 exec, exec, s[0:1]
	v_lshlrev_b32_e32 v0, 16, v2
	v_fma_f32 v18, -v221, v62, v0
	v_lshlrev_b32_e32 v0, 16, v4
	s_waitcnt lgkmcnt(0)
	v_fma_f32 v13, -v221, v46, v0
	v_lshlrev_b32_e32 v0, 16, v6
	v_fma_f32 v12, -v221, v30, v0
	v_lshlrev_b32_e32 v0, 16, v8
	v_fma_f32 v0, -v221, v14, v0
	v_mul_f32_e32 v10, v13, v13
	v_mul_f32_e32 v11, v0, v0
	v_fmac_f32_e32 v10, v18, v18
	v_fmac_f32_e32 v11, v12, v12
	v_add_f32_e32 v10, v10, v11
	s_nop 1
	v_add_f32_dpp v10, v10, v10 quad_perm:[1,0,3,2] row_mask:0xf bank_mask:0xf
	s_nop 1
	v_add_f32_dpp v10, v10, v10 quad_perm:[2,3,0,1] row_mask:0xf bank_mask:0xf
	s_nop 1
	v_add_f32_dpp v10, v10, v10 row_half_mirror row_mask:0xf bank_mask:0xf
	ds_swizzle_b32 v11, v10 offset:swizzle(SWAP,8)
	s_waitcnt lgkmcnt(0)
	v_add_f32_e32 v11, v10, v11
	ds_swizzle_b32 v14, v11 offset:swizzle(SWAP,16)
	v_or_b32_e32 v10, 24, v76
	v_cmp_gt_i32_e32 vcc, s2, v10
	s_and_saveexec_b64 s[0:1], vcc
	s_cbranch_execz .LBB0_309
	s_waitcnt lgkmcnt(0)
	v_add_f32_e32 v11, v11, v14
	v_fmamk_f32 v11, v11, 0x3c000000, v215
	v_rsq_f32_e32 v14, v11
	v_ashrrev_i32_e32 v11, 31, v10
	v_lshlrev_b64 v[10:11], 12, v[10:11]
	v_lshl_add_u64 v[10:11], v[20:21], 0, v[10:11]
	v_mul_f32_e32 v18, v14, v18
	v_mul_f32_e32 v18, v80, v18
	v_bfe_u32 v19, v18, 16, 1
	v_mul_f32_e32 v13, v14, v13
	v_add3_u32 v18, v18, v19, s31
	v_mul_f32_e32 v13, v82, v13
	global_store_short_d16_hi v[10:11], v18, off
	v_bfe_u32 v18, v13, 16, 1
	v_mul_f32_e32 v12, v14, v12
	v_add3_u32 v13, v13, v18, s31
	v_mul_f32_e32 v12, v84, v12
	global_store_short_d16_hi v[10:11], v13, off offset:64
	v_bfe_u32 v13, v12, 16, 1
	v_mul_f32_e32 v0, v14, v0
	v_add3_u32 v12, v12, v13, s31
	v_mul_f32_e32 v0, v102, v0
	global_store_short_d16_hi v[10:11], v12, off offset:128
	v_bfe_u32 v12, v0, 16, 1
	v_add3_u32 v0, v0, v12, s31
	global_store_short_d16_hi v[10:11], v0, off offset:192
; __device__ __forceinline__ int crow(int r, int hi) { return (r & 3) + 8 * (r >> 2) + 4 * hi; }
; #define SWZ(v, pat) __int_as_float(__builtin_amdgcn_ds_swizzle(__float_as_int(v), (pat)))
; __device__ __forceinline__ unsigned f2bf(float f) { unsigned u = __builtin_bit_cast(unsigned, f); return (u + 0x7fffu + ((u >> 16) & 1u)) >> 16; }
; __global__ void __launch_bounds__(NWAVES * 64) fwd_kernel(Args args) {
;     ...
;                         for (int r = 0; r < 16; ++r) { float s2 = (o[0][r] * o[0][r] + o[1][r] * o[1][r]) + (o[2][r] * o[2][r] + o[3][r] * o[3][r]);
;                             s2 += SWZ(s2, 0x041F); s2 += SWZ(s2, 0x081F); s2 += SWZ(s2, 0x101F); s2 += SWZ(s2, 0x201F); s2 += SWZ(s2, 0x401F);
;                             const float rn = __builtin_amdgcn_rsqf(s2 * (1.0f / 128.0f) + EPS); const int row = qw0 + att::crow(r, hi);
;                             if (row < Lk) { bf16_t* yp = Ys + (size_t)row * DM + head * 128 + r32;
; #pragma unroll
;                                 for (int d = 0; d < 4; ++d) ((__attribute__((address_space(1))) bf16_t*)yp)[d * 32] = (bf16_t)f2bf(o[d][r] * rn * g4[d]); } }
.LBB0_309:
	s_or_b64 exec, exec, s[0:1]
	v_and_b32_e32 v0, 0xffff0000, v2
	v_fma_f32 v12, -v221, v63, v0
	v_and_b32_e32 v0, 0xffff0000, v4
	v_fma_f32 v4, -v221, v47, v0
	v_and_b32_e32 v0, 0xffff0000, v6
	v_fma_f32 v2, -v221, v31, v0
	v_and_b32_e32 v0, 0xffff0000, v8
	v_fma_f32 v0, -v221, v15, v0
	v_mul_f32_e32 v6, v4, v4
	v_mul_f32_e32 v8, v0, v0
	v_fmac_f32_e32 v6, v12, v12
	v_fmac_f32_e32 v8, v2, v2
	v_add_f32_e32 v6, v6, v8
	ds_swizzle_b32 v8, v6 offset:swizzle(SWAP,1)
	v_or_b32_e32 v10, 25, v76
	v_cmp_gt_i32_e32 vcc, s2, v10
	s_waitcnt lgkmcnt(0)
	v_add_f32_e32 v6, v6, v8
	s_nop 1
	v_add_f32_dpp v6, v6, v6 quad_perm:[2,3,0,1] row_mask:0xf bank_mask:0xf
	s_nop 1
	v_add_f32_dpp v6, v6, v6 row_half_mirror row_mask:0xf bank_mask:0xf
	s_nop 1
	v_add_f32_dpp v6, v6, v6 row_mirror row_mask:0xf bank_mask:0xf
	ds_swizzle_b32 v8, v6 offset:swizzle(SWAP,16)
	s_and_saveexec_b64 s[0:1], vcc
	s_cbranch_execz .LBB0_311
	s_waitcnt lgkmcnt(0)
	v_add_f32_e32 v6, v6, v8
	v_fmamk_f32 v6, v6, 0x3c000000, v215
	v_rsq_f32_e32 v6, v6
	v_ashrrev_i32_e32 v11, 31, v10
	v_lshlrev_b64 v[10:11], 12, v[10:11]
	v_lshl_add_u64 v[10:11], v[20:21], 0, v[10:11]
	v_mul_f32_e32 v8, v6, v12
	v_mul_f32_e32 v8, v80, v8
	v_bfe_u32 v12, v8, 16, 1
	v_mul_f32_e32 v4, v6, v4
	v_add3_u32 v8, v8, v12, s31
	v_mul_f32_e32 v4, v82, v4
	global_store_short_d16_hi v[10:11], v8, off
	v_bfe_u32 v8, v4, 16, 1
	v_mul_f32_e32 v2, v6, v2
	v_add3_u32 v4, v4, v8, s31
	v_mul_f32_e32 v2, v84, v2
	global_store_short_d16_hi v[10:11], v4, off offset:64
	v_bfe_u32 v4, v2, 16, 1
	v_mul_f32_e32 v0, v6, v0
	v_add3_u32 v2, v2, v4, s31
	v_mul_f32_e32 v0, v102, v0
	global_store_short_d16_hi v[10:11], v2, off offset:128
	v_bfe_u32 v2, v0, 16, 1
	v_add3_u32 v0, v0, v2, s31
	global_store_short_d16_hi v[10:11], v0, off offset:192
.LBB0_311:
	s_or_b64 exec, exec, s[0:1]
	v_lshlrev_b32_e32 v0, 16, v3
	v_fma_f32 v6, -v221, v64, v0
	v_lshlrev_b32_e32 v0, 16, v5
	v_fma_f32 v4, -v221, v48, v0
	v_lshlrev_b32_e32 v0, 16, v7
	v_fma_f32 v2, -v221, v32, v0
	v_lshlrev_b32_e32 v0, 16, v9
	v_fma_f32 v0, -v221, v16, v0
	s_waitcnt lgkmcnt(0)
	v_mul_f32_e32 v8, v4, v4
	v_mul_f32_e32 v10, v0, v0
	v_fmac_f32_e32 v8, v6, v6
	v_fmac_f32_e32 v10, v2, v2
	v_add_f32_e32 v8, v8, v10
	s_nop 1
	v_add_f32_dpp v8, v8, v8 quad_perm:[1,0,3,2] row_mask:0xf bank_mask:0xf
	s_nop 1
	v_add_f32_dpp v8, v8, v8 quad_perm:[2,3,0,1] row_mask:0xf bank_mask:0xf
	s_nop 1
	v_add_f32_dpp v8, v8, v8 row_half_mirror row_mask:0xf bank_mask:0xf
	ds_swizzle_b32 v10, v8 offset:swizzle(SWAP,8)
	s_waitcnt lgkmcnt(0)
	v_add_f32_e32 v8, v8, v10
	ds_swizzle_b32 v11, v8 offset:swizzle(SWAP,16)
	v_or_b32_e32 v10, 26, v76
	v_cmp_gt_i32_e32 vcc, s2, v10
	s_and_saveexec_b64 s[0:1], vcc
	s_cbranch_execz .LBB0_313
	s_waitcnt lgkmcnt(0)
	v_add_f32_e32 v8, v8, v11
	v_fmamk_f32 v8, v8, 0x3c000000, v215
	v_rsq_f32_e32 v8, v8
	v_ashrrev_i32_e32 v11, 31, v10
	v_lshlrev_b64 v[10:11], 12, v[10:11]
	v_lshl_add_u64 v[10:11], v[20:21], 0, v[10:11]
	v_mul_f32_e32 v6, v8, v6
	v_mul_f32_e32 v6, v80, v6
	v_bfe_u32 v12, v6, 16, 1
	v_mul_f32_e32 v4, v8, v4
	v_add3_u32 v6, v6, v12, s31
	v_mul_f32_e32 v4, v82, v4
	global_store_short_d16_hi v[10:11], v6, off
	v_bfe_u32 v6, v4, 16, 1
	v_mul_f32_e32 v2, v8, v2
	v_add3_u32 v4, v4, v6, s31
	v_mul_f32_e32 v2, v84, v2
	global_store_short_d16_hi v[10:11], v4, off offset:64
	v_bfe_u32 v4, v2, 16, 1
	v_mul_f32_e32 v0, v8, v0
	v_add3_u32 v2, v2, v4, s31
	v_mul_f32_e32 v0, v102, v0
	global_store_short_d16_hi v[10:11], v2, off offset:128
	v_bfe_u32 v2, v0, 16, 1
	v_add3_u32 v0, v0, v2, s31
	global_store_short_d16_hi v[10:11], v0, off offset:192
.LBB0_313:
	s_or_b64 exec, exec, s[0:1]
	v_and_b32_e32 v0, 0xffff0000, v3
	v_fma_f32 v6, -v221, v65, v0
	v_and_b32_e32 v0, 0xffff0000, v5
	v_fma_f32 v5, -v221, v49, v0
	v_and_b32_e32 v0, 0xffff0000, v7
	v_fma_f32 v4, -v221, v33, v0
	v_and_b32_e32 v0, 0xffff0000, v9
	v_fma_f32 v0, -v221, v17, v0
	v_mul_f32_e32 v2, v5, v5
	v_mul_f32_e32 v3, v0, v0
	v_fmac_f32_e32 v2, v6, v6
	v_fmac_f32_e32 v3, v4, v4
	v_add_f32_e32 v2, v2, v3
	ds_swizzle_b32 v3, v2 offset:swizzle(SWAP,1)
	s_waitcnt lgkmcnt(0)
	v_add_f32_e32 v2, v2, v3
	s_nop 1
	v_add_f32_dpp v2, v2, v2 quad_perm:[2,3,0,1] row_mask:0xf bank_mask:0xf
	s_nop 1
	v_add_f32_dpp v2, v2, v2 row_half_mirror row_mask:0xf bank_mask:0xf
	ds_swizzle_b32 v3, v2 offset:swizzle(SWAP,8)
	s_waitcnt lgkmcnt(0)
	v_add_f32_e32 v7, v2, v3
	ds_swizzle_b32 v8, v7 offset:swizzle(SWAP,16)
	v_or_b32_e32 v2, 27, v76
	v_cmp_gt_i32_e32 vcc, s2, v2
	s_and_saveexec_b64 s[0:1], vcc
	s_xor_b64 s[0:1], exec, s[0:1]
	s_cbranch_execz .LBB0_315
	s_waitcnt lgkmcnt(0)
	v_add_f32_e32 v3, v7, v8
	v_fmamk_f32 v3, v3, 0x3c000000, v215
	v_rsq_f32_e32 v7, v3
	v_ashrrev_i32_e32 v3, 31, v2
	v_lshlrev_b64 v[2:3], 12, v[2:3]
	v_lshl_add_u64 v[10:11], v[20:21], 0, v[2:3]
	v_mul_f32_e32 v2, v7, v6
	v_mul_f32_e32 v2, v80, v2
	v_bfe_u32 v3, v2, 16, 1
	v_add3_u32 v2, v2, v3, s31
	global_store_short_d16_hi v[10:11], v2, off
	v_mul_f32_e32 v2, v7, v5
	v_mul_f32_e32 v2, v82, v2
	v_bfe_u32 v3, v2, 16, 1
	v_add3_u32 v2, v2, v3, s31
	global_store_short_d16_hi v[10:11], v2, off offset:64
	v_mul_f32_e32 v2, v7, v4
	v_mul_f32_e32 v2, v84, v2
	v_bfe_u32 v3, v2, 16, 1
	v_mul_f32_e32 v0, v7, v0
	v_add3_u32 v2, v2, v3, s31
	v_mul_f32_e32 v3, v102, v0
	s_or_b64 s[28:29], s[28:29], exec
	global_store_short_d16_hi v[10:11], v2, off offset:128

; __device__ __forceinline__ int crow(int r, int hi) { return (r & 3) + 8 * (r >> 2) + 4 * hi; }
; #define SWZ(v, pat) __int_as_float(__builtin_amdgcn_ds_swizzle(__float_as_int(v), (pat)))
; __device__ __forceinline__ unsigned f2bf(float f) { unsigned u = __builtin_bit_cast(unsigned, f); return (u + 0x7fffu + ((u >> 16) & 1u)) >> 16; }
; __global__ void __launch_bounds__(NWAVES * 64) fwd_kernel(Args args) {
;     ...
;                         for (int r = 0; r < 16; ++r) { float s2 = (o[0][r] * o[0][r] + o[1][r] * o[1][r]) + (o[2][r] * o[2][r] + o[3][r] * o[3][r]);
;                             s2 += SWZ(s2, 0x041F); s2 += SWZ(s2, 0x081F); s2 += SWZ(s2, 0x101F); s2 += SWZ(s2, 0x201F); s2 += SWZ(s2, 0x401F);
;                             const float rn = __builtin_amdgcn_rsqf(s2 * (1.0f / 128.0f) + EPS); const int row = qw0 + att::crow(r, hi);
;                             if (row < Lk) { bf16_t* yp = Ys + (size_t)row * DM + head * 128 + r32;
; #pragma unroll
;                                 for (int d = 0; d < 4; ++d) ((__attribute__((address_space(1))) bf16_t*)yp)[d * 32] = (bf16_t)f2bf(o[d][r] * rn * g4[d]); } }
.LBB0_339:
	s_or_b64 exec, exec, s[0:1]
	v_fma_f32 v51, -v221, v59, v51
	v_fma_f32 v10, -v221, v11, v3
	s_waitcnt lgkmcnt(0)
	v_fma_f32 v57, -v221, v71, v73
	v_fma_f32 v19, -v221, v27, v19
	v_mul_f32_e32 v2, v51, v51
	v_mul_f32_e32 v3, v10, v10
	v_fmac_f32_e32 v2, v57, v57
	v_fmac_f32_e32 v3, v19, v19
	v_add_f32_e32 v2, v2, v3
	s_nop 1
	v_add_f32_dpp v2, v2, v2 quad_perm:[1,0,3,2] row_mask:0xf bank_mask:0xf
	s_nop 1
	v_add_f32_dpp v2, v2, v2 quad_perm:[2,3,0,1] row_mask:0xf bank_mask:0xf
	s_nop 1
	v_add_f32_dpp v2, v2, v2 row_half_mirror row_mask:0xf bank_mask:0xf
	ds_swizzle_b32 v3, v2 offset:swizzle(SWAP,8)
	s_waitcnt lgkmcnt(0)
	v_add_f32_e32 v3, v2, v3
	ds_swizzle_b32 v11, v3 offset:swizzle(SWAP,16)
	v_or_b32_e32 v2, 1, v56
	v_cmp_gt_i32_e32 vcc, s2, v2
	s_and_saveexec_b64 s[0:1], vcc
	s_cbranch_execz .LBB0_341
	s_waitcnt lgkmcnt(0)
	v_add_f32_e32 v3, v3, v11
	v_fmamk_f32 v3, v3, 0x3c000000, v215
	v_rsq_f32_e32 v11, v3
	v_ashrrev_i32_e32 v3, 31, v2
	v_lshlrev_b64 v[2:3], 12, v[2:3]
	v_lshl_add_u64 v[2:3], v[54:55], 0, v[2:3]
	v_mul_f32_e32 v27, v11, v57
	v_mul_f32_e32 v27, v50, v27
	v_bfe_u32 v57, v27, 16, 1
	v_add3_u32 v27, v27, v57, s31
	global_store_short_d16_hi v[2:3], v27, off
	v_mul_f32_e32 v27, v11, v51
	v_mul_f32_e32 v27, v26, v27
	v_bfe_u32 v51, v27, 16, 1
	v_mul_f32_e32 v19, v11, v19
	v_mul_f32_e32 v10, v11, v10
	v_add3_u32 v27, v27, v51, s31
	v_mul_f32_e32 v19, v18, v19
	v_mul_f32_e32 v10, v0, v10
	global_store_short_d16_hi v[2:3], v27, off offset:64
	v_bfe_u32 v27, v19, 16, 1
	v_bfe_u32 v11, v10, 16, 1
	v_add3_u32 v19, v19, v27, s31
	v_add3_u32 v10, v10, v11, s31
	global_store_short_d16_hi v[2:3], v19, off offset:128
	global_store_short_d16_hi v[2:3], v10, off offset:192
.LBB0_341:
	s_or_b64 exec, exec, s[0:1]
	s_waitcnt lgkmcnt(0)
	v_fma_f32 v11, -v221, v60, v52
	v_fma_f32 v4, -v221, v12, v4
	v_fma_f32 v19, -v221, v66, v68
	v_fma_f32 v10, -v221, v28, v20
	v_mul_f32_e32 v2, v11, v11
	v_mul_f32_e32 v3, v4, v4
	v_fmac_f32_e32 v2, v19, v19
	v_fmac_f32_e32 v3, v10, v10
	v_add_f32_e32 v2, v2, v3
	s_nop 1
	v_add_f32_dpp v2, v2, v2 quad_perm:[1,0,3,2] row_mask:0xf bank_mask:0xf
	s_nop 1
	v_add_f32_dpp v2, v2, v2 quad_perm:[2,3,0,1] row_mask:0xf bank_mask:0xf
	s_nop 1
	v_add_f32_dpp v2, v2, v2 row_half_mirror row_mask:0xf bank_mask:0xf
	ds_swizzle_b32 v3, v2 offset:swizzle(SWAP,8)
	s_waitcnt lgkmcnt(0)
	v_add_f32_e32 v3, v2, v3
	ds_swizzle_b32 v12, v3 offset:swizzle(SWAP,16)
	v_or_b32_e32 v2, 2, v56
	v_cmp_gt_i32_e32 vcc, s2, v2
	s_and_saveexec_b64 s[0:1], vcc
	s_cbranch_execz .LBB0_343
	s_waitcnt lgkmcnt(0)
	v_add_f32_e32 v3, v3, v12
	v_fmamk_f32 v3, v3, 0x3c000000, v215
	v_rsq_f32_e32 v12, v3
	v_ashrrev_i32_e32 v3, 31, v2
	v_lshlrev_b64 v[2:3], 12, v[2:3]
	v_lshl_add_u64 v[2:3], v[54:55], 0, v[2:3]
	v_mul_f32_e32 v19, v12, v19
	v_mul_f32_e32 v19, v50, v19
	v_bfe_u32 v20, v19, 16, 1
	v_mul_f32_e32 v11, v12, v11
	v_add3_u32 v19, v19, v20, s31
	v_mul_f32_e32 v11, v26, v11
	global_store_short_d16_hi v[2:3], v19, off
	v_bfe_u32 v19, v11, 16, 1
	v_mul_f32_e32 v10, v12, v10
	v_add3_u32 v11, v11, v19, s31
	v_mul_f32_e32 v10, v18, v10
	global_store_short_d16_hi v[2:3], v11, off offset:64
	v_bfe_u32 v11, v10, 16, 1
	v_mul_f32_e32 v4, v12, v4
	v_add3_u32 v10, v10, v11, s31
	v_mul_f32_e32 v4, v0, v4
	global_store_short_d16_hi v[2:3], v10, off offset:128
	v_bfe_u32 v10, v4, 16, 1
	v_add3_u32 v4, v4, v10, s31
	global_store_short_d16_hi v[2:3], v4, off offset:192
.LBB0_343:
	s_or_b64 exec, exec, s[0:1]
	v_fma_f32 v11, -v221, v61, v53
	v_fma_f32 v4, -v221, v13, v5
	s_waitcnt lgkmcnt(0)
	v_fma_f32 v12, -v221, v67, v69
	v_fma_f32 v10, -v221, v29, v21
	v_mul_f32_e32 v2, v11, v11
	v_mul_f32_e32 v3, v4, v4
	v_fmac_f32_e32 v2, v12, v12
	v_fmac_f32_e32 v3, v10, v10
	v_add_f32_e32 v2, v2, v3
	s_nop 1
	v_add_f32_dpp v2, v2, v2 quad_perm:[1,0,3,2] row_mask:0xf bank_mask:0xf
	s_nop 1
	v_add_f32_dpp v2, v2, v2 quad_perm:[2,3,0,1] row_mask:0xf bank_mask:0xf
	s_nop 1
	v_add_f32_dpp v2, v2, v2 row_half_mirror row_mask:0xf bank_mask:0xf
	ds_swizzle_b32 v3, v2 offset:swizzle(SWAP,8)
	s_waitcnt lgkmcnt(0)
	v_add_f32_e32 v3, v2, v3
	ds_swizzle_b32 v5, v3 offset:swizzle(SWAP,16)
	v_or_b32_e32 v2, 3, v56
	v_cmp_gt_i32_e32 vcc, s2, v2
	s_and_saveexec_b64 s[0:1], vcc
	s_cbranch_execz .LBB0_345
	s_waitcnt lgkmcnt(0)
	v_add_f32_e32 v3, v3, v5
	v_fmamk_f32 v3, v3, 0x3c000000, v215
	v_rsq_f32_e32 v5, v3
	v_ashrrev_i32_e32 v3, 31, v2
	v_lshlrev_b64 v[2:3], 12, v[2:3]
	v_lshl_add_u64 v[2:3], v[54:55], 0, v[2:3]
	v_mul_f32_e32 v12, v5, v12
	v_mul_f32_e32 v12, v50, v12
	v_bfe_u32 v13, v12, 16, 1
	v_mul_f32_e32 v11, v5, v11
	v_add3_u32 v12, v12, v13, s31
	v_mul_f32_e32 v11, v26, v11
	global_store_short_d16_hi v[2:3], v12, off
	v_bfe_u32 v12, v11, 16, 1
	v_mul_f32_e32 v10, v5, v10
	v_mul_f32_e32 v4, v5, v4
	v_add3_u32 v11, v11, v12, s31
	v_mul_f32_e32 v10, v18, v10
	v_mul_f32_e32 v4, v0, v4
	global_store_short_d16_hi v[2:3], v11, off offset:64
	v_bfe_u32 v11, v10, 16, 1
	v_bfe_u32 v5, v4, 16, 1
	v_add3_u32 v10, v10, v11, s31
	v_add3_u32 v4, v4, v5, s31
	global_store_short_d16_hi v[2:3], v10, off offset:128
	global_store_short_d16_hi v[2:3], v4, off offset:192
; __device__ __forceinline__ int crow(int r, int hi) { return (r & 3) + 8 * (r >> 2) + 4 * hi; }
; #define SWZ(v, pat) __int_as_float(__builtin_amdgcn_ds_swizzle(__float_as_int(v), (pat)))
; __device__ __forceinline__ unsigned f2bf(float f) { unsigned u = __builtin_bit_cast(unsigned, f); return (u + 0x7fffu + ((u >> 16) & 1u)) >> 16; }
; __global__ void __launch_bounds__(NWAVES * 64) fwd_kernel(Args args) {
;     ...
;                         for (int r = 0; r < 16; ++r) { float s2 = (o[0][r] * o[0][r] + o[1][r] * o[1][r]) + (o[2][r] * o[2][r] + o[3][r] * o[3][r]);
;                             s2 += SWZ(s2, 0x041F); s2 += SWZ(s2, 0x081F); s2 += SWZ(s2, 0x101F); s2 += SWZ(s2, 0x201F); s2 += SWZ(s2, 0x401F);
;                             const float rn = __builtin_amdgcn_rsqf(s2 * (1.0f / 128.0f) + EPS); const int row = qw0 + att::crow(r, hi);
;                             if (row < Lk) { bf16_t* yp = Ys + (size_t)row * DM + head * 128 + r32;
; #pragma unroll
;                                 for (int d = 0; d < 4; ++d) ((__attribute__((address_space(1))) bf16_t*)yp)[d * 32] = (bf16_t)f2bf(o[d][r] * rn * g4[d]); } }
.LBB0_345:
	s_or_b64 exec, exec, s[0:1]
	v_fma_f32 v10, -v221, v38, v42
	v_fma_f32 v4, -v221, v14, v6
	v_fma_f32 v11, -v221, v46, v44
	s_waitcnt lgkmcnt(0)
	v_fma_f32 v5, -v221, v30, v22
	v_mul_f32_e32 v2, v10, v10
	v_mul_f32_e32 v3, v4, v4
	v_fmac_f32_e32 v2, v11, v11
	v_fmac_f32_e32 v3, v5, v5
	v_add_f32_e32 v2, v2, v3
	s_nop 1
	v_add_f32_dpp v2, v2, v2 quad_perm:[1,0,3,2] row_mask:0xf bank_mask:0xf
	s_nop 1
	v_add_f32_dpp v2, v2, v2 quad_perm:[2,3,0,1] row_mask:0xf bank_mask:0xf
	s_nop 1
	v_add_f32_dpp v2, v2, v2 row_half_mirror row_mask:0xf bank_mask:0xf
	ds_swizzle_b32 v3, v2 offset:swizzle(SWAP,8)
	s_waitcnt lgkmcnt(0)
	v_add_f32_e32 v3, v2, v3
	ds_swizzle_b32 v6, v3 offset:swizzle(SWAP,16)
	v_or_b32_e32 v2, 8, v56
	v_cmp_gt_i32_e32 vcc, s2, v2
	s_and_saveexec_b64 s[0:1], vcc
	s_cbranch_execz .LBB0_347
	s_waitcnt lgkmcnt(0)
	v_add_f32_e32 v3, v3, v6
	v_fmamk_f32 v3, v3, 0x3c000000, v215
	v_rsq_f32_e32 v6, v3
	v_ashrrev_i32_e32 v3, 31, v2
	v_lshlrev_b64 v[2:3], 12, v[2:3]
	v_lshl_add_u64 v[2:3], v[54:55], 0, v[2:3]
	v_mul_f32_e32 v11, v6, v11
	v_mul_f32_e32 v11, v50, v11
	v_bfe_u32 v12, v11, 16, 1
	v_mul_f32_e32 v10, v6, v10
	v_add3_u32 v11, v11, v12, s31
	v_mul_f32_e32 v10, v26, v10
	global_store_short_d16_hi v[2:3], v11, off
	v_bfe_u32 v11, v10, 16, 1
	v_mul_f32_e32 v5, v6, v5
	v_add3_u32 v10, v10, v11, s31
	v_mul_f32_e32 v5, v18, v5
	global_store_short_d16_hi v[2:3], v10, off offset:64
	v_bfe_u32 v10, v5, 16, 1
	v_mul_f32_e32 v4, v6, v4
	v_add3_u32 v5, v5, v10, s31
	v_mul_f32_e32 v4, v0, v4
	global_store_short_d16_hi v[2:3], v5, off offset:128
	v_bfe_u32 v5, v4, 16, 1
	v_add3_u32 v4, v4, v5, s31
	global_store_short_d16_hi v[2:3], v4, off offset:192
.LBB0_347:
	s_or_b64 exec, exec, s[0:1]
	s_waitcnt lgkmcnt(0)
	v_fma_f32 v6, -v221, v39, v43
	v_fma_f32 v4, -v221, v15, v7
	v_fma_f32 v10, -v221, v47, v45
	v_fma_f32 v5, -v221, v31, v23
	v_mul_f32_e32 v2, v6, v6
	v_mul_f32_e32 v3, v4, v4
	v_fmac_f32_e32 v2, v10, v10
	v_fmac_f32_e32 v3, v5, v5
	v_add_f32_e32 v2, v2, v3
	s_nop 1
	v_add_f32_dpp v2, v2, v2 quad_perm:[1,0,3,2] row_mask:0xf bank_mask:0xf
	s_nop 1
	v_add_f32_dpp v2, v2, v2 quad_perm:[2,3,0,1] row_mask:0xf bank_mask:0xf
	s_nop 1
	v_add_f32_dpp v2, v2, v2 row_half_mirror row_mask:0xf bank_mask:0xf
	ds_swizzle_b32 v3, v2 offset:swizzle(SWAP,8)
	s_waitcnt lgkmcnt(0)
	v_add_f32_e32 v3, v2, v3
	ds_swizzle_b32 v7, v3 offset:swizzle(SWAP,16)
	v_or_b32_e32 v2, 9, v56
	v_cmp_gt_i32_e32 vcc, s2, v2
	s_and_saveexec_b64 s[0:1], vcc
	s_cbranch_execz .LBB0_349
	s_waitcnt lgkmcnt(0)
	v_add_f32_e32 v3, v3, v7
	v_fmamk_f32 v3, v3, 0x3c000000, v215
	v_rsq_f32_e32 v7, v3
	v_ashrrev_i32_e32 v3, 31, v2
	v_lshlrev_b64 v[2:3], 12, v[2:3]
	v_lshl_add_u64 v[2:3], v[54:55], 0, v[2:3]
	v_mul_f32_e32 v10, v7, v10
	v_mul_f32_e32 v10, v50, v10
	v_bfe_u32 v11, v10, 16, 1
	v_mul_f32_e32 v6, v7, v6
	v_add3_u32 v10, v10, v11, s31
	v_mul_f32_e32 v6, v26, v6
	global_store_short_d16_hi v[2:3], v10, off
	v_bfe_u32 v10, v6, 16, 1
	v_mul_f32_e32 v5, v7, v5
	v_add3_u32 v6, v6, v10, s31
	v_mul_f32_e32 v5, v18, v5
	global_store_short_d16_hi v[2:3], v6, off offset:64
	v_bfe_u32 v6, v5, 16, 1
	v_mul_f32_e32 v4, v7, v4
	v_add3_u32 v5, v5, v6, s31
	v_mul_f32_e32 v4, v0, v4
	global_store_short_d16_hi v[2:3], v5, off offset:128
	v_bfe_u32 v5, v4, 16, 1
	v_add3_u32 v4, v4, v5, s31
	global_store_short_d16_hi v[2:3], v4, off offset:192
.LBB0_349:
	s_or_b64 exec, exec, s[0:1]
	v_fma_f32 v6, -v221, v34, v36
	v_fma_f32 v4, -v221, v16, v8
	s_waitcnt lgkmcnt(0)
	v_fma_f32 v7, -v221, v48, v40
	v_fma_f32 v5, -v221, v32, v24
	v_mul_f32_e32 v2, v6, v6
	v_mul_f32_e32 v3, v4, v4
	v_fmac_f32_e32 v2, v7, v7
	v_fmac_f32_e32 v3, v5, v5
	v_add_f32_e32 v2, v2, v3
	s_nop 1
	v_add_f32_dpp v2, v2, v2 quad_perm:[1,0,3,2] row_mask:0xf bank_mask:0xf
	s_nop 1
	v_add_f32_dpp v2, v2, v2 quad_perm:[2,3,0,1] row_mask:0xf bank_mask:0xf
	s_nop 1
	v_add_f32_dpp v2, v2, v2 row_half_mirror row_mask:0xf bank_mask:0xf
	ds_swizzle_b32 v3, v2 offset:swizzle(SWAP,8)
	s_waitcnt lgkmcnt(0)
	v_add_f32_e32 v3, v2, v3
	ds_swizzle_b32 v8, v3 offset:swizzle(SWAP,16)
	v_or_b32_e32 v2, 10, v56
	v_cmp_gt_i32_e32 vcc, s2, v2
	s_and_saveexec_b64 s[0:1], vcc
	s_cbranch_execz .LBB0_351
	s_waitcnt lgkmcnt(0)
	v_add_f32_e32 v3, v3, v8
	v_fmamk_f32 v3, v3, 0x3c000000, v215
	v_rsq_f32_e32 v8, v3
	v_ashrrev_i32_e32 v3, 31, v2
	v_lshlrev_b64 v[2:3], 12, v[2:3]
	v_lshl_add_u64 v[2:3], v[54:55], 0, v[2:3]
	v_mul_f32_e32 v7, v8, v7
	v_mul_f32_e32 v7, v50, v7
	v_bfe_u32 v10, v7, 16, 1
	v_mul_f32_e32 v6, v8, v6
	v_add3_u32 v7, v7, v10, s31
	v_mul_f32_e32 v6, v26, v6
	global_store_short_d16_hi v[2:3], v7, off
	v_bfe_u32 v7, v6, 16, 1
	v_mul_f32_e32 v5, v8, v5
	v_add3_u32 v6, v6, v7, s31
	v_mul_f32_e32 v5, v18, v5
	global_store_short_d16_hi v[2:3], v6, off offset:64
	v_bfe_u32 v6, v5, 16, 1
	v_mul_f32_e32 v4, v8, v4
	v_add3_u32 v5, v5, v6, s31
	v_mul_f32_e32 v4, v0, v4
	global_store_short_d16_hi v[2:3], v5, off offset:128
	v_bfe_u32 v5, v4, 16, 1
	v_add3_u32 v4, v4, v5, s31
	global_store_short_d16_hi v[2:3], v4, off offset:192
.LBB0_351:
	s_or_b64 exec, exec, s[0:1]
	v_fma_f32 v6, -v221, v35, v37
	v_fma_f32 v4, -v221, v17, v9
	v_fma_f32 v7, -v221, v49, v41
	v_fma_f32 v5, -v221, v33, v25
	v_mul_f32_e32 v2, v6, v6
	v_mul_f32_e32 v3, v4, v4
	v_fmac_f32_e32 v2, v7, v7
	v_fmac_f32_e32 v3, v5, v5
	v_add_f32_e32 v2, v2, v3
	ds_swizzle_b32 v3, v2 offset:swizzle(SWAP,1)
	s_waitcnt lgkmcnt(0)
	v_add_f32_e32 v2, v2, v3
	s_nop 1
	v_add_f32_dpp v2, v2, v2 quad_perm:[2,3,0,1] row_mask:0xf bank_mask:0xf
	s_nop 1
	v_add_f32_dpp v2, v2, v2 row_half_mirror row_mask:0xf bank_mask:0xf
	ds_swizzle_b32 v3, v2 offset:swizzle(SWAP,8)
	s_waitcnt lgkmcnt(0)
	v_add_f32_e32 v8, v2, v3
	ds_swizzle_b32 v9, v8 offset:swizzle(SWAP,16)
	v_or_b32_e32 v2, 11, v56
	v_cmp_gt_i32_e32 vcc, s2, v2
	s_and_saveexec_b64 s[0:1], vcc
	s_cbranch_execz .LBB0_353
	s_waitcnt lgkmcnt(0)
	v_add_f32_e32 v3, v8, v9
	v_fmamk_f32 v3, v3, 0x3c000000, v215
	v_rsq_f32_e32 v8, v3
	v_ashrrev_i32_e32 v3, 31, v2
	v_lshlrev_b64 v[2:3], 12, v[2:3]
	v_lshl_add_u64 v[10:11], v[54:55], 0, v[2:3]
	v_mul_f32_e32 v2, v8, v7
	v_mul_f32_e32 v2, v50, v2
	v_bfe_u32 v3, v2, 16, 1
	v_add3_u32 v2, v2, v3, s31
	global_store_short_d16_hi v[10:11], v2, off
	v_mul_f32_e32 v2, v8, v6
	v_mul_f32_e32 v2, v26, v2
	v_bfe_u32 v3, v2, 16, 1
	v_add3_u32 v2, v2, v3, s31
	global_store_short_d16_hi v[10:11], v2, off offset:64
	v_mul_f32_e32 v2, v8, v5
	v_mul_f32_e32 v2, v18, v2
	v_bfe_u32 v3, v2, 16, 1
	v_add3_u32 v2, v2, v3, s31
	global_store_short_d16_hi v[10:11], v2, off offset:128
	v_mul_f32_e32 v2, v8, v4
	v_mul_f32_e32 v3, v0, v2
	s_or_b64 s[28:29], s[28:29], exec

; __device__ __forceinline__ float bf_lo(unsigned w) { return __uint_as_float(w << 16); }
; __device__ __forceinline__ float bf_hi(unsigned w) { return __uint_as_float(w & 0xffff0000u); }
; __device__ __forceinline__ unsigned pk2(float lo, float hi) { return f2bf(lo) | (f2bf(hi) << 16); }
; __device__ __forceinline__ float wave_sum(float v) {
;     ...
;     v += WS_SWZ(v, 0x041F); v += WS_SWZ(v, 0x081F); v += WS_SWZ(v, 0x101F); v += WS_SWZ(v, 0x201F); v += WS_SWZ(v, 0x401F);
;     ...
;     auto rr = __builtin_amdgcn_permlane32_swap(__float_as_uint(v), __float_as_uint(v), false, false);
;     return __uint_as_float(rr[0]) + __uint_as_float(rr[1]);
; }
; __global__ void __launch_bounds__(NWAVES * 64) fwd_kernel(Args args) {
;     ...
;             for (int r = gw; r < MREAL; r += NGW) {
;                 const int t = r < 4 * LP ? r % LP : r - 4 * LP;
;                 float c = 1.f, sn = 0.f;
;                 if (t >= NMETA) { const int pp = t - NMETA, rowi = pp >> 6, coli = pp & 63;
;                     const float f = __builtin_amdgcn_exp2f(-(float)(lane & 31) * (13.287712379549449f / 32.0f));
;                     const float ang = (float)(lane < 32 ? rowi : coli) * f; float rev = ang * 0.15915494309189535f; rev -= floorf(rev);
;                     sn = __builtin_amdgcn_sinf(rev); c = __builtin_amdgcn_cosf(rev); }
;                 bf16_t* base = QKV + (size_t)r * NIN;
;                 unsigned wv[10];
; #pragma unroll
;                 for (int hh = 0; hh < 10; ++hh) wv[hh] = *((const unsigned*)(base + (hh < 8 ? 3072 + hh * 128 : 4096 + (hh - 8) * 128)) + lane);
;                 const float gq0 = qkg[2 * lane], gq1 = qkg[2 * lane + 1], gk0 = qkg[128 + 2 * lane], gk1 = qkg[128 + 2 * lane + 1];
; #pragma unroll
;                 for (int hh = 0; hh < 10; ++hh) { const int off = hh < 8 ? 3072 + hh * 128 : 4096 + (hh - 8) * 128; const float qs = hh < 8 ? QSCALE_B : 1.f;
;                     const float x0 = pg8::bf_lo(wv[hh]), x1 = pg8::bf_hi(wv[hh]);
;                     const float s2 = wave_sum(x0 * x0 + x1 * x1); const float rn = __builtin_amdgcn_rsqf(s2 * (1.0f / 128.0f) + EPS);
;                     const float y0 = x0 * rn * (hh < 8 ? gq0 : gk0), y1 = x1 * rn * (hh < 8 ? gq1 : gk1);
;                     *((unsigned*)(base + off) + lane) = pk2((y0 * c - y1 * sn) * qs, (y0 * sn + y1 * c) * qs); }
;             }
.LBB0_414:
	flat_load_dword v17, v[6:7]
	flat_load_dword v18, v[6:7] offset:256
	flat_load_dword v19, v[6:7] offset:512
	flat_load_dword v16, v[6:7] offset:768
	flat_load_dword v15, v[6:7] offset:1024
	flat_load_dword v14, v[6:7] offset:1280
	flat_load_dword v13, v[6:7] offset:1536
	flat_load_dword v12, v[6:7] offset:1792
	flat_load_dword v11, v[6:7] offset:2048
	flat_load_dword v10, v[6:7] offset:2304
	s_add_i32 s4, s4, s47
	s_cmpk_gt_i32 s4, 0x604f
	s_waitcnt vmcnt(0) lgkmcnt(0)
	v_lshlrev_b32_e32 v20, 16, v17
	v_and_b32_e32 v17, 0xffff0000, v17
	v_mul_f32_e32 v21, v17, v17
	v_fmac_f32_e32 v21, v20, v20
	s_nop 1
	v_add_f32_dpp v21, v21, v21 quad_perm:[1,0,3,2] row_mask:0xf bank_mask:0xf
	s_nop 1
	v_add_f32_dpp v21, v21, v21 quad_perm:[2,3,0,1] row_mask:0xf bank_mask:0xf
	s_nop 1
	v_add_f32_dpp v21, v21, v21 row_half_mirror row_mask:0xf bank_mask:0xf
	s_nop 1
	v_add_f32_dpp v21, v21, v21 row_mirror row_mask:0xf bank_mask:0xf
	ds_swizzle_b32 v22, v21 offset:swizzle(SWAP,16)
	s_waitcnt lgkmcnt(0)
	v_add_f32_e32 v21, v21, v22
	v_mov_b32_e32 v22, v21
	s_nop 1
	v_permlane32_swap_b32_e32 v21, v22
	v_add_f32_e32 v21, v21, v22
	v_fmamk_f32 v21, v21, 0x3c000000, v215
	v_rsq_f32_e32 v21, v21
	s_nop 0
	v_mul_f32_e32 v17, v21, v17
	v_mul_f32_e32 v20, v21, v20
	v_mul_f32_e32 v17, v3, v17
	v_mul_f32_e32 v20, v2, v20
	v_mul_f32_e32 v21, v0, v17
	v_fma_f32 v21, v9, v20, -v21
	v_mul_f32_e32 v17, v9, v17
	v_mul_f32_e32 v21, 0x3e0293ee, v21
	v_fmac_f32_e32 v17, v0, v20
	v_mul_f32_e32 v17, 0x3e0293ee, v17
	v_bfe_u32 v20, v21, 16, 1
	v_add3_u32 v20, v21, v20, s31
	v_bfe_u32 v21, v17, 16, 1
	v_lshrrev_b32_e32 v20, 16, v20
	v_add3_u32 v17, v17, v21, s31
	v_and_or_b32 v17, v17, s71, v20
	flat_store_dword v[6:7], v17
	v_lshlrev_b32_e32 v17, 16, v18
	v_and_b32_e32 v18, 0xffff0000, v18
	v_mul_f32_e32 v20, v18, v18
	v_fmac_f32_e32 v20, v17, v17
	s_nop 1
	v_add_f32_dpp v20, v20, v20 quad_perm:[1,0,3,2] row_mask:0xf bank_mask:0xf
	s_nop 1
	v_add_f32_dpp v20, v20, v20 quad_perm:[2,3,0,1] row_mask:0xf bank_mask:0xf
	s_nop 1
	v_add_f32_dpp v20, v20, v20 row_half_mirror row_mask:0xf bank_mask:0xf
	s_nop 1
	v_add_f32_dpp v20, v20, v20 row_mirror row_mask:0xf bank_mask:0xf
	ds_swizzle_b32 v21, v20 offset:swizzle(SWAP,16)
	s_waitcnt lgkmcnt(0)
	v_add_f32_e32 v20, v20, v21
	v_mov_b32_e32 v21, v20
	s_nop 1
	v_permlane32_swap_b32_e32 v20, v21
	v_add_f32_e32 v20, v20, v21
	v_fmamk_f32 v20, v20, 0x3c000000, v215
	v_rsq_f32_e32 v20, v20
	s_nop 0
	v_mul_f32_e32 v18, v20, v18
	v_mul_f32_e32 v17, v20, v17
	v_mul_f32_e32 v18, v3, v18
	v_mul_f32_e32 v17, v2, v17
	v_mul_f32_e32 v20, v0, v18
	v_fma_f32 v20, v9, v17, -v20
	v_mul_f32_e32 v18, v9, v18
	v_mul_f32_e32 v20, 0x3e0293ee, v20
	v_fmac_f32_e32 v18, v0, v17
	v_mul_f32_e32 v17, 0x3e0293ee, v18
	v_bfe_u32 v18, v20, 16, 1
	v_add3_u32 v18, v20, v18, s31
	v_bfe_u32 v20, v17, 16, 1
	v_lshrrev_b32_e32 v18, 16, v18
	v_add3_u32 v17, v17, v20, s31
	v_and_or_b32 v17, v17, s71, v18
	v_and_b32_e32 v18, 0xffff0000, v19
	flat_store_dword v[6:7], v17 offset:256
	v_lshlrev_b32_e32 v17, 16, v19
	v_mul_f32_e32 v19, v18, v18
	v_fmac_f32_e32 v19, v17, v17
	s_nop 1
	v_add_f32_dpp v19, v19, v19 quad_perm:[1,0,3,2] row_mask:0xf bank_mask:0xf
	s_nop 1
	v_add_f32_dpp v19, v19, v19 quad_perm:[2,3,0,1] row_mask:0xf bank_mask:0xf
	s_nop 1
	v_add_f32_dpp v19, v19, v19 row_half_mirror row_mask:0xf bank_mask:0xf
	s_nop 1
	v_add_f32_dpp v19, v19, v19 row_mirror row_mask:0xf bank_mask:0xf
	ds_swizzle_b32 v20, v19 offset:swizzle(SWAP,16)
	s_waitcnt lgkmcnt(0)
	v_add_f32_e32 v19, v19, v20
	v_mov_b32_e32 v20, v19
	s_nop 1
	v_permlane32_swap_b32_e32 v19, v20
	v_add_f32_e32 v19, v19, v20
	v_fmamk_f32 v19, v19, 0x3c000000, v215
	v_rsq_f32_e32 v19, v19
	s_nop 0
	v_mul_f32_e32 v18, v19, v18
	v_mul_f32_e32 v17, v19, v17
	v_mul_f32_e32 v18, v3, v18
	v_mul_f32_e32 v17, v2, v17
	v_mul_f32_e32 v19, v0, v18
	v_fma_f32 v19, v9, v17, -v19
	v_mul_f32_e32 v18, v9, v18
	v_mul_f32_e32 v19, 0x3e0293ee, v19
	v_fmac_f32_e32 v18, v0, v17
	v_mul_f32_e32 v17, 0x3e0293ee, v18
	v_bfe_u32 v18, v19, 16, 1
	v_add3_u32 v18, v19, v18, s31
	v_bfe_u32 v19, v17, 16, 1
	v_lshrrev_b32_e32 v18, 16, v18
	v_add3_u32 v17, v17, v19, s31
	v_and_or_b32 v17, v17, s71, v18
	flat_store_dword v[6:7], v17 offset:512
	v_lshlrev_b32_e32 v17, 16, v16
	v_and_b32_e32 v16, 0xffff0000, v16
	v_mul_f32_e32 v18, v16, v16
	v_fmac_f32_e32 v18, v17, v17
	s_nop 1
	v_add_f32_dpp v18, v18, v18 quad_perm:[1,0,3,2] row_mask:0xf bank_mask:0xf
	s_nop 1
	v_add_f32_dpp v18, v18, v18 quad_perm:[2,3,0,1] row_mask:0xf bank_mask:0xf
	s_nop 1
	v_add_f32_dpp v18, v18, v18 row_half_mirror row_mask:0xf bank_mask:0xf
	s_nop 1
	v_add_f32_dpp v18, v18, v18 row_mirror row_mask:0xf bank_mask:0xf
	ds_swizzle_b32 v19, v18 offset:swizzle(SWAP,16)
	s_waitcnt lgkmcnt(0)
	v_add_f32_e32 v18, v18, v19
	v_mov_b32_e32 v19, v18
	s_nop 1
	v_permlane32_swap_b32_e32 v18, v19
	v_add_f32_e32 v18, v18, v19
	v_fmamk_f32 v18, v18, 0x3c000000, v215
	v_rsq_f32_e32 v18, v18
	s_nop 0
	v_mul_f32_e32 v16, v18, v16
	v_mul_f32_e32 v17, v18, v17
	v_mul_f32_e32 v16, v3, v16
	v_mul_f32_e32 v17, v2, v17
	v_mul_f32_e32 v18, v0, v16
	v_fma_f32 v18, v9, v17, -v18
	v_mul_f32_e32 v16, v9, v16
	v_mul_f32_e32 v18, 0x3e0293ee, v18
	v_fmac_f32_e32 v16, v0, v17
	v_mul_f32_e32 v16, 0x3e0293ee, v16
	v_bfe_u32 v17, v18, 16, 1
	v_add3_u32 v17, v18, v17, s31
	v_bfe_u32 v18, v16, 16, 1
	v_lshrrev_b32_e32 v17, 16, v17
	v_add3_u32 v16, v16, v18, s31
	v_and_or_b32 v16, v16, s71, v17
	flat_store_dword v[6:7], v16 offset:768
	v_lshlrev_b32_e32 v16, 16, v15
	v_and_b32_e32 v15, 0xffff0000, v15
	v_mul_f32_e32 v17, v15, v15
	v_fmac_f32_e32 v17, v16, v16
	s_nop 1
	v_add_f32_dpp v17, v17, v17 quad_perm:[1,0,3,2] row_mask:0xf bank_mask:0xf
	s_nop 1
	v_add_f32_dpp v17, v17, v17 quad_perm:[2,3,0,1] row_mask:0xf bank_mask:0xf
	s_nop 1
	v_add_f32_dpp v17, v17, v17 row_half_mirror row_mask:0xf bank_mask:0xf
	s_nop 1
	v_add_f32_dpp v17, v17, v17 row_mirror row_mask:0xf bank_mask:0xf
	ds_swizzle_b32 v18, v17 offset:swizzle(SWAP,16)
	s_waitcnt lgkmcnt(0)
; __device__ __forceinline__ float bf_lo(unsigned w) { return __uint_as_float(w << 16); }
; __device__ __forceinline__ float bf_hi(unsigned w) { return __uint_as_float(w & 0xffff0000u); }
; __device__ __forceinline__ unsigned pk2(float lo, float hi) { return f2bf(lo) | (f2bf(hi) << 16); }
; #define WS_SWZ(x, pat) __int_as_float(__builtin_amdgcn_ds_swizzle(__float_as_int(x), (pat)))
; __device__ __forceinline__ float wave_sum(float v) {
;     ...
;     v += WS_SWZ(v, 0x041F); v += WS_SWZ(v, 0x081F); v += WS_SWZ(v, 0x101F); v += WS_SWZ(v, 0x201F); v += WS_SWZ(v, 0x401F);
;     ...
;     auto rr = __builtin_amdgcn_permlane32_swap(__float_as_uint(v), __float_as_uint(v), false, false);
;     return __uint_as_float(rr[0]) + __uint_as_float(rr[1]);
; }
; __global__ void __launch_bounds__(NWAVES * 64) fwd_kernel(Args args) {
;     ...
; #pragma unroll
;                 for (int hh = 0; hh < 10; ++hh) { const int off = hh < 8 ? 3072 + hh * 128 : 4096 + (hh - 8) * 128; const float qs = hh < 8 ? QSCALE_B : 1.f;
;                     const float x0 = pg8::bf_lo(wv[hh]), x1 = pg8::bf_hi(wv[hh]);
;                     const float s2 = wave_sum(x0 * x0 + x1 * x1); const float rn = __builtin_amdgcn_rsqf(s2 * (1.0f / 128.0f) + EPS);
;                     const float y0 = x0 * rn * (hh < 8 ? gq0 : gk0), y1 = x1 * rn * (hh < 8 ? gq1 : gk1);
;                     *((unsigned*)(base + off) + lane) = pk2((y0 * c - y1 * sn) * qs, (y0 * sn + y1 * c) * qs); }
	v_add_f32_e32 v17, v17, v18
	v_mov_b32_e32 v18, v17
	s_nop 1
	v_permlane32_swap_b32_e32 v17, v18
	v_add_f32_e32 v17, v17, v18
	v_fmamk_f32 v17, v17, 0x3c000000, v215
	v_rsq_f32_e32 v17, v17
	s_nop 0
	v_mul_f32_e32 v15, v17, v15
	v_mul_f32_e32 v16, v17, v16
	v_mul_f32_e32 v15, v3, v15
	v_mul_f32_e32 v16, v2, v16
	v_mul_f32_e32 v17, v0, v15
	v_fma_f32 v17, v9, v16, -v17
	v_mul_f32_e32 v15, v9, v15
	v_mul_f32_e32 v17, 0x3e0293ee, v17
	v_fmac_f32_e32 v15, v0, v16
	v_mul_f32_e32 v15, 0x3e0293ee, v15
	v_bfe_u32 v16, v17, 16, 1
	v_add3_u32 v16, v17, v16, s31
	v_bfe_u32 v17, v15, 16, 1
	v_lshrrev_b32_e32 v16, 16, v16
	v_add3_u32 v15, v15, v17, s31
	v_and_or_b32 v15, v15, s71, v16
	flat_store_dword v[6:7], v15 offset:1024
	v_lshlrev_b32_e32 v15, 16, v14
	v_and_b32_e32 v14, 0xffff0000, v14
	v_mul_f32_e32 v16, v14, v14
	v_fmac_f32_e32 v16, v15, v15
	s_nop 1
	v_add_f32_dpp v16, v16, v16 quad_perm:[1,0,3,2] row_mask:0xf bank_mask:0xf
	s_nop 1
	v_add_f32_dpp v16, v16, v16 quad_perm:[2,3,0,1] row_mask:0xf bank_mask:0xf
	s_nop 1
	v_add_f32_dpp v16, v16, v16 row_half_mirror row_mask:0xf bank_mask:0xf
	s_nop 1
	v_add_f32_dpp v16, v16, v16 row_mirror row_mask:0xf bank_mask:0xf
	ds_swizzle_b32 v17, v16 offset:swizzle(SWAP,16)
	s_waitcnt lgkmcnt(0)
	v_add_f32_e32 v16, v16, v17
	v_mov_b32_e32 v17, v16
	s_nop 1
	v_permlane32_swap_b32_e32 v16, v17
	v_add_f32_e32 v16, v16, v17
	v_fmamk_f32 v16, v16, 0x3c000000, v215
	v_rsq_f32_e32 v16, v16
	s_nop 0
	v_mul_f32_e32 v14, v16, v14
	v_mul_f32_e32 v15, v16, v15
	v_mul_f32_e32 v14, v3, v14
	v_mul_f32_e32 v15, v2, v15
	v_mul_f32_e32 v16, v0, v14
	v_fma_f32 v16, v9, v15, -v16
	v_mul_f32_e32 v14, v9, v14
	v_mul_f32_e32 v16, 0x3e0293ee, v16
	v_fmac_f32_e32 v14, v0, v15
	v_mul_f32_e32 v14, 0x3e0293ee, v14
	v_bfe_u32 v15, v16, 16, 1
	v_add3_u32 v15, v16, v15, s31
	v_bfe_u32 v16, v14, 16, 1
	v_lshrrev_b32_e32 v15, 16, v15
	v_add3_u32 v14, v14, v16, s31
	v_and_or_b32 v14, v14, s71, v15
	flat_store_dword v[6:7], v14 offset:1280
	v_lshlrev_b32_e32 v14, 16, v13
	v_and_b32_e32 v13, 0xffff0000, v13
	v_mul_f32_e32 v15, v13, v13
	v_fmac_f32_e32 v15, v14, v14
	s_nop 1
	v_add_f32_dpp v15, v15, v15 quad_perm:[1,0,3,2] row_mask:0xf bank_mask:0xf
	s_nop 1
	v_add_f32_dpp v15, v15, v15 quad_perm:[2,3,0,1] row_mask:0xf bank_mask:0xf
	s_nop 1
	v_add_f32_dpp v15, v15, v15 row_half_mirror row_mask:0xf bank_mask:0xf
	s_nop 1
	v_add_f32_dpp v15, v15, v15 row_mirror row_mask:0xf bank_mask:0xf
	ds_swizzle_b32 v16, v15 offset:swizzle(SWAP,16)
	s_waitcnt lgkmcnt(0)
	v_add_f32_e32 v15, v15, v16
	v_mov_b32_e32 v16, v15
	s_nop 1
	v_permlane32_swap_b32_e32 v15, v16
	v_add_f32_e32 v15, v15, v16
	v_fmamk_f32 v15, v15, 0x3c000000, v215
	v_rsq_f32_e32 v15, v15
	s_nop 0
	v_mul_f32_e32 v13, v15, v13
	v_mul_f32_e32 v14, v15, v14
	v_mul_f32_e32 v13, v3, v13
	v_mul_f32_e32 v14, v2, v14
	v_mul_f32_e32 v15, v0, v13
	v_fma_f32 v15, v9, v14, -v15
	v_mul_f32_e32 v13, v9, v13
	v_mul_f32_e32 v15, 0x3e0293ee, v15
	v_fmac_f32_e32 v13, v0, v14
	v_mul_f32_e32 v13, 0x3e0293ee, v13
	v_bfe_u32 v14, v15, 16, 1
	v_add3_u32 v14, v15, v14, s31
	v_bfe_u32 v15, v13, 16, 1
	v_lshrrev_b32_e32 v14, 16, v14
	v_add3_u32 v13, v13, v15, s31
	v_and_or_b32 v13, v13, s71, v14
	flat_store_dword v[6:7], v13 offset:1536
	v_lshlrev_b32_e32 v13, 16, v12
	v_and_b32_e32 v12, 0xffff0000, v12
	v_mul_f32_e32 v14, v12, v12
	v_fmac_f32_e32 v14, v13, v13
	s_nop 1
	v_add_f32_dpp v14, v14, v14 quad_perm:[1,0,3,2] row_mask:0xf bank_mask:0xf
	s_nop 1
	v_add_f32_dpp v14, v14, v14 quad_perm:[2,3,0,1] row_mask:0xf bank_mask:0xf
	s_nop 1
	v_add_f32_dpp v14, v14, v14 row_half_mirror row_mask:0xf bank_mask:0xf
	s_nop 1
	v_add_f32_dpp v14, v14, v14 row_mirror row_mask:0xf bank_mask:0xf
	ds_swizzle_b32 v15, v14 offset:swizzle(SWAP,16)
	s_waitcnt lgkmcnt(0)
	v_add_f32_e32 v14, v14, v15
	v_mov_b32_e32 v15, v14
	s_nop 1
	v_permlane32_swap_b32_e32 v14, v15
	v_add_f32_e32 v14, v14, v15
	v_fmamk_f32 v14, v14, 0x3c000000, v215
	v_rsq_f32_e32 v14, v14
	s_nop 0
	v_mul_f32_e32 v12, v14, v12
	v_mul_f32_e32 v13, v14, v13
	v_mul_f32_e32 v12, v3, v12
	v_mul_f32_e32 v13, v2, v13
	v_mul_f32_e32 v14, v0, v12
	v_fma_f32 v14, v9, v13, -v14
	v_mul_f32_e32 v12, v9, v12
	v_mul_f32_e32 v14, 0x3e0293ee, v14
	v_fmac_f32_e32 v12, v0, v13
	v_mul_f32_e32 v12, 0x3e0293ee, v12
	v_bfe_u32 v13, v14, 16, 1
	v_add3_u32 v13, v14, v13, s31
	v_bfe_u32 v14, v12, 16, 1
	v_lshrrev_b32_e32 v13, 16, v13
	v_add3_u32 v12, v12, v14, s31
	v_and_or_b32 v12, v12, s71, v13
	flat_store_dword v[6:7], v12 offset:1792
	v_lshlrev_b32_e32 v12, 16, v11
	v_and_b32_e32 v11, 0xffff0000, v11
	v_mul_f32_e32 v13, v11, v11
	v_fmac_f32_e32 v13, v12, v12
	s_nop 1
	v_add_f32_dpp v13, v13, v13 quad_perm:[1,0,3,2] row_mask:0xf bank_mask:0xf
	s_nop 1
	v_add_f32_dpp v13, v13, v13 quad_perm:[2,3,0,1] row_mask:0xf bank_mask:0xf
	s_nop 1
	v_add_f32_dpp v13, v13, v13 row_half_mirror row_mask:0xf bank_mask:0xf
	s_nop 1
	v_add_f32_dpp v13, v13, v13 row_mirror row_mask:0xf bank_mask:0xf
	ds_swizzle_b32 v14, v13 offset:swizzle(SWAP,16)
	s_waitcnt lgkmcnt(0)
	v_add_f32_e32 v13, v13, v14
	v_mov_b32_e32 v14, v13
	s_nop 1
	v_permlane32_swap_b32_e32 v13, v14
	v_add_f32_e32 v13, v13, v14
	v_fmamk_f32 v13, v13, 0x3c000000, v215
	v_rsq_f32_e32 v13, v13
	s_nop 0
	v_mul_f32_e32 v11, v13, v11
	v_mul_f32_e32 v12, v13, v12
	v_mul_f32_e32 v11, v5, v11
	v_mul_f32_e32 v12, v4, v12
	v_mul_f32_e32 v13, v0, v11
	v_fma_f32 v13, v9, v12, -v13
	v_mul_f32_e32 v11, v9, v11
	v_fmac_f32_e32 v11, v0, v12
	v_bfe_u32 v12, v13, 16, 1
	v_add3_u32 v12, v13, v12, s31
	v_bfe_u32 v13, v11, 16, 1
	v_lshrrev_b32_e32 v12, 16, v12
	v_add3_u32 v11, v11, v13, s31
	v_and_or_b32 v11, v11, s71, v12
	flat_store_dword v[6:7], v11 offset:2048
	v_lshlrev_b32_e32 v11, 16, v10
	v_and_b32_e32 v10, 0xffff0000, v10
	v_mul_f32_e32 v12, v10, v10
	v_fmac_f32_e32 v12, v11, v11
	s_nop 1
	v_add_f32_dpp v12, v12, v12 quad_perm:[1,0,3,2] row_mask:0xf bank_mask:0xf
	s_nop 1
	v_add_f32_dpp v12, v12, v12 quad_perm:[2,3,0,1] row_mask:0xf bank_mask:0xf
	s_nop 1
	v_add_f32_dpp v12, v12, v12 row_half_mirror row_mask:0xf bank_mask:0xf
	s_nop 1
	v_add_f32_dpp v12, v12, v12 row_mirror row_mask:0xf bank_mask:0xf
	ds_swizzle_b32 v13, v12 offset:swizzle(SWAP,16)
	s_waitcnt lgkmcnt(0)
	v_add_f32_e32 v12, v12, v13
	v_mov_b32_e32 v13, v12
	s_nop 1
	v_permlane32_swap_b32_e32 v12, v13
	v_add_f32_e32 v12, v12, v13
	v_fmamk_f32 v12, v12, 0x3c000000, v215
	v_rsq_f32_e32 v12, v12
	s_nop 0
	v_mul_f32_e32 v10, v12, v10
	v_mul_f32_e32 v11, v12, v11
	v_mul_f32_e32 v10, v5, v10
	v_mul_f32_e32 v11, v4, v11
	v_mul_f32_e32 v12, v0, v10
	v_fma_f32 v12, v9, v11, -v12
	v_mul_f32_e32 v9, v9, v10
	v_fmac_f32_e32 v9, v0, v11
	v_bfe_u32 v0, v12, 16, 1
	v_add3_u32 v0, v12, v0, s31
	v_bfe_u32 v10, v9, 16, 1
	v_lshrrev_b32_e32 v0, 16, v0
	v_add3_u32 v9, v9, v10, s31
	v_and_or_b32 v0, v9, s71, v0
	flat_store_dword v[6:7], v0 offset:2304
	v_lshl_add_u64 v[6:7], v[6:7], 0, s[0:1]
	s_cbranch_scc1 .LBB0_421

; __device__ __forceinline__ float bf_lo(unsigned w) { return __uint_as_float(w << 16); }
; __device__ __forceinline__ float bf_hi(unsigned w) { return __uint_as_float(w & 0xffff0000u); }
; __device__ __forceinline__ unsigned pk2(float lo, float hi) { return f2bf(lo) | (f2bf(hi) << 16); }
; #define WS_SWZ(x, pat) __int_as_float(__builtin_amdgcn_ds_swizzle(__float_as_int(x), (pat)))
; __device__ __forceinline__ float wave_sum(float v) {
;     ...
;     v += WS_SWZ(v, 0x041F); v += WS_SWZ(v, 0x081F); v += WS_SWZ(v, 0x101F); v += WS_SWZ(v, 0x201F); v += WS_SWZ(v, 0x401F);
;     ...
;     auto rr = __builtin_amdgcn_permlane32_swap(__float_as_uint(v), __float_as_uint(v), false, false);
;     return __uint_as_float(rr[0]) + __uint_as_float(rr[1]);
; }
; __global__ void __launch_bounds__(NWAVES * 64) fwd_kernel(Args args) {
;     ...
;                   bf16_t* hp = HB + (size_t)(MFULL + row) * DM + c8; const v4u h = *(const v4u*)hp;
;                   const float n0 = pg8::bf_lo(h.x) + alpha * s0.x, n1 = pg8::bf_hi(h.x) + alpha * s0.y, n2 = pg8::bf_lo(h.y) + alpha * s0.z, n3 = pg8::bf_hi(h.y) + alpha * s0.w;
;                   const float n4 = pg8::bf_lo(h.z) + alpha * s1.x, n5 = pg8::bf_hi(h.z) + alpha * s1.y, n6 = pg8::bf_lo(h.w) + alpha * s1.z, n7 = pg8::bf_hi(h.w) + alpha * s1.w;
;                   v4u w; w.x = pk2(n0, n1); w.y = pk2(n2, n3); w.z = pk2(n4, n5); w.w = pk2(n6, n7); *(v4u*)hp = w;
;                   const float sq = wave_sum((n0 * n0 + n1 * n1) + (n2 * n2 + n3 * n3) + (n4 * n4 + n5 * n5) + (n6 * n6 + n7 * n7));
;                   if ((ltid_ & 63) == 0) atomicAdd(ssn + MFULL + row, sq); } }
.LBB0_554:
	v_readlane_b32 s6, v254, 25
	v_lshlrev_b64 v[6:7], 12, v[2:3]
	v_readlane_b32 s7, v254, 26
	v_mov_b32_e32 v21, v12
	v_mov_b32_e32 v12, v15
	v_lshl_add_u64 v[6:7], s[6:7], 0, v[6:7]
	v_lshl_add_u64 v[4:5], v[4:5], 1, v[6:7]
	v_add_co_u32_e32 v16, vcc, 0x6000000, v4
	v_mov_b32_e32 v20, v14
	s_nop 0
	v_addc_co_u32_e32 v17, vcc, 0, v5, vcc
	flat_load_dwordx4 v[4:7], v[16:17]
	v_mov_b32_e32 v14, v10
	v_mov_b32_e32 v15, v8
	v_mov_b32_e32 v8, v11
	s_waitcnt vmcnt(0) lgkmcnt(0)
	v_lshlrev_b32_e32 v19, 16, v5
	v_lshlrev_b32_e32 v18, 16, v4
	v_and_b32_e32 v5, 0xffff0000, v5
	v_and_b32_e32 v4, 0xffff0000, v4
	v_pk_fma_f32 v[12:13], v[158:159], v[12:13], v[4:5]
	v_lshlrev_b32_e32 v5, 16, v7
	v_lshlrev_b32_e32 v4, 16, v6
	v_pk_fma_f32 v[18:19], v[158:159], v[20:21], v[18:19]
	v_pk_fma_f32 v[14:15], v[158:159], v[14:15], v[4:5]
	v_and_b32_e32 v5, 0xffff0000, v7
	v_and_b32_e32 v4, 0xffff0000, v6
	v_bfe_u32 v6, v13, 16, 1
	v_bfe_u32 v7, v12, 16, 1
	v_pk_fma_f32 v[8:9], v[158:159], v[8:9], v[4:5]
	v_add3_u32 v10, v12, v7, s31
	v_add3_u32 v11, v13, v6, s31
	v_bfe_u32 v6, v18, 16, 1
	v_bfe_u32 v7, v19, 16, 1
	v_bfe_u32 v20, v14, 16, 1
	v_bfe_u32 v21, v15, 16, 1
	v_bfe_u32 v4, v9, 16, 1
	v_bfe_u32 v5, v8, 16, 1
	v_add3_u32 v21, v15, v21, s31
	v_add3_u32 v20, v14, v20, s31
	v_add3_u32 v7, v19, v7, s31
	v_add3_u32 v6, v18, v6, s31
	v_add3_u32 v5, v8, v5, s31
	v_add3_u32 v4, v9, v4, s31
	v_lshrrev_b32_e32 v22, 16, v6
	v_lshrrev_b32_e32 v23, 16, v7
	v_lshrrev_b32_e32 v6, 16, v20
	v_lshrrev_b32_e32 v7, 16, v21
	v_and_or_b32 v7, v4, s71, v7
	v_and_or_b32 v6, v5, s71, v6
	v_and_or_b32 v5, v11, s71, v23
	v_and_or_b32 v4, v10, s71, v22
	flat_store_dwordx4 v[16:17], v[4:7]
	s_nop 1
	v_pk_mul_f32 v[4:5], v[12:13], v[12:13]
	v_pk_mul_f32 v[6:7], v[8:9], v[8:9]
	v_pk_fma_f32 v[4:5], v[18:19], v[18:19], v[4:5]
	v_pk_fma_f32 v[6:7], v[14:15], v[14:15], v[6:7]
	v_add_f32_e32 v4, v4, v5
	v_add_f32_e32 v4, v6, v4
	v_add_f32_e32 v4, v7, v4
	s_nop 1
	v_add_f32_dpp v4, v4, v4 quad_perm:[1,0,3,2] row_mask:0xf bank_mask:0xf
	s_nop 1
	v_add_f32_dpp v4, v4, v4 quad_perm:[2,3,0,1] row_mask:0xf bank_mask:0xf
	s_nop 1
	v_add_f32_dpp v4, v4, v4 row_half_mirror row_mask:0xf bank_mask:0xf
	s_nop 1
	v_add_f32_dpp v4, v4, v4 row_mirror row_mask:0xf bank_mask:0xf
	ds_swizzle_b32 v5, v4 offset:swizzle(SWAP,16)
	s_waitcnt lgkmcnt(0)
	v_add_f32_e32 v4, v4, v5
	v_mov_b32_e32 v5, v4
	s_nop 1
	v_permlane32_swap_b32_e32 v4, v5
	s_and_saveexec_b64 s[6:7], s[40:41]
	s_cbranch_execz .LBB0_551
	v_lshl_add_u64 v[2:3], v[2:3], 2, s[0:1]
	v_add_f32_e32 v4, v4, v5
	flat_atomic_add_f32 v[2:3], v4
	s_branch .LBB0_551

; __device__ __forceinline__ unsigned pk2(float lo, float hi) { return f2bf(lo) | (f2bf(hi) << 16); }
; #define WS_SWZ(x, pat) __int_as_float(__builtin_amdgcn_ds_swizzle(__float_as_int(x), (pat)))
; __device__ __forceinline__ float wave_sum(float v) {
;     ...
;     v += WS_SWZ(v, 0x041F); v += WS_SWZ(v, 0x081F); v += WS_SWZ(v, 0x101F); v += WS_SWZ(v, 0x201F); v += WS_SWZ(v, 0x401F);
;     ...
;     auto rr = __builtin_amdgcn_permlane32_swap(__float_as_uint(v), __float_as_uint(v), false, false);
;     return __uint_as_float(rr[0]) + __uint_as_float(rr[1]);
; }
; __global__ void __launch_bounds__(NWAVES * 64) fwd_kernel(Args args) {
;     ...
;             for (int r = gw; r < MPAD; r += NGW) {
;                 unsigned long long* o8 = (unsigned long long*)(HB + (size_t)r * DM) + lane; float s2 = 0.f;
;                 if (r < MREAL) {
;                     const int s = r < 4 * LP ? r / LP : 4, t = r < 4 * LP ? r % LP : r - 4 * LP;
;                     const float* src = t < NMETA ? meta + (size_t)t * DM : (s < 4 ? x_prompt + ((size_t)s * 2048 + (t - NMETA)) * DM : x_sample + (size_t)(t - NMETA) * DM);
;                     const f32x4* xr = (const f32x4*)src + lane;
; #pragma unroll
;                     for (int j = 0; j < 8; ++j) { const f32x4 v = __builtin_nontemporal_load(xr + 64 * j); s2 += (v.x * v.x + v.y * v.y) + (v.z * v.z + v.w * v.w);
;                         o8[64 * j] = (unsigned long long)pk2(v.x, v.y) | ((unsigned long long)pk2(v.z, v.w) << 32); }
;                     s2 = wave_sum(s2);
.LBB0_648:
	s_lshl_b64 s[10:11], s[14:15], 13
	s_add_u32 s10, s12, s10
	s_addc_u32 s11, s13, s11
	global_load_dwordx4 v[10:13], v0, s[10:11] nt
	v_lshl_add_u64 v[26:27], s[10:11], 0, v[0:1]
	v_readlane_b32 s16, v254, 27
	v_readlane_b32 s17, v254, 28
	s_waitcnt vmcnt(0)
	v_bfe_u32 v3, v10, 16, 1
	v_bfe_u32 v14, v12, 16, 1
	v_bfe_u32 v5, v11, 16, 1
	v_bfe_u32 v15, v13, 16, 1
	v_add3_u32 v3, v10, v3, s31
	v_add3_u32 v14, v12, v14, s31
	v_add3_u32 v5, v11, v5, s31
	v_add3_u32 v15, v13, v15, s31
	v_lshrrev_b32_e32 v3, 16, v3
	v_lshrrev_b32_e32 v16, 16, v14
	v_and_or_b32 v14, v5, s71, v3
	v_and_or_b32 v15, v15, s71, v16
	flat_store_dwordx2 v[8:9], v[14:15]
	global_load_dwordx4 v[14:17], v0, s[10:11] offset:1024 nt
	v_mov_b32_e32 v44, v13
	s_waitcnt vmcnt(0)
	v_bfe_u32 v3, v14, 16, 1
	v_bfe_u32 v18, v16, 16, 1
	v_bfe_u32 v5, v15, 16, 1
	v_bfe_u32 v19, v17, 16, 1
	v_add3_u32 v3, v14, v3, s31
	v_add3_u32 v18, v16, v18, s31
	v_add3_u32 v5, v15, v5, s31
	v_add3_u32 v19, v17, v19, s31
	v_lshrrev_b32_e32 v3, 16, v3
	v_lshrrev_b32_e32 v20, 16, v18
	v_and_or_b32 v18, v5, s71, v3
	v_and_or_b32 v19, v19, s71, v20
	flat_store_dwordx2 v[8:9], v[18:19] offset:512
	global_load_dwordx4 v[18:21], v0, s[10:11] offset:2048 nt
	v_mov_b32_e32 v43, v15
	v_mov_b32_e32 v45, v17
	v_mov_b32_e32 v13, v16
	v_pk_mul_f32 v[16:17], v[44:45], v[44:45]
	s_waitcnt vmcnt(0)
	v_bfe_u32 v3, v18, 16, 1
	v_bfe_u32 v22, v20, 16, 1
	v_bfe_u32 v5, v19, 16, 1
	v_bfe_u32 v23, v21, 16, 1
	v_add3_u32 v3, v18, v3, s31
	v_add3_u32 v22, v20, v22, s31
	v_add3_u32 v5, v19, v5, s31
	v_add3_u32 v23, v21, v23, s31
	v_lshrrev_b32_e32 v3, 16, v3
	v_lshrrev_b32_e32 v24, 16, v22
	v_and_or_b32 v22, v5, s71, v3
	v_and_or_b32 v23, v23, s71, v24
	flat_store_dwordx2 v[8:9], v[22:23] offset:1024
	global_load_dwordx4 v[22:25], v0, s[10:11] offset:3072 nt
	s_movk_i32 s10, 0x1000
	v_add_co_u32_e32 v38, vcc, s10, v26
	v_pk_fma_f32 v[12:13], v[12:13], v[12:13], v[16:17]
	s_nop 0
	v_addc_co_u32_e32 v39, vcc, 0, v27, vcc
	s_waitcnt vmcnt(0)
	v_bfe_u32 v3, v22, 16, 1
	v_bfe_u32 v26, v24, 16, 1
	v_bfe_u32 v5, v23, 16, 1
	v_bfe_u32 v27, v25, 16, 1
	v_add3_u32 v3, v22, v3, s31
	v_add3_u32 v26, v24, v26, s31
	v_add3_u32 v5, v23, v5, s31
	v_add3_u32 v27, v25, v27, s31
	v_lshrrev_b32_e32 v3, 16, v3
	v_lshrrev_b32_e32 v28, 16, v26
	v_and_or_b32 v26, v5, s71, v3
	v_and_or_b32 v27, v27, s71, v28
	flat_store_dwordx2 v[8:9], v[26:27] offset:1536
	global_load_dwordx4 v[26:29], v[38:39], off nt
	s_waitcnt vmcnt(0)
	v_bfe_u32 v3, v26, 16, 1
	v_bfe_u32 v30, v28, 16, 1
	v_bfe_u32 v5, v27, 16, 1
	v_bfe_u32 v31, v29, 16, 1
	v_add3_u32 v3, v26, v3, s31
	v_add3_u32 v30, v28, v30, s31
	v_add3_u32 v5, v27, v5, s31
	v_add3_u32 v31, v29, v31, s31
	v_lshrrev_b32_e32 v3, 16, v3
	v_lshrrev_b32_e32 v32, 16, v30
	v_and_or_b32 v30, v5, s71, v3
	v_and_or_b32 v31, v31, s71, v32
	flat_store_dwordx2 v[8:9], v[30:31] offset:2048
	global_load_dwordx4 v[30:33], v[38:39], off offset:1024 nt
	s_waitcnt vmcnt(0)
	v_bfe_u32 v3, v30, 16, 1
	v_bfe_u32 v34, v32, 16, 1
	v_bfe_u32 v5, v31, 16, 1
	v_bfe_u32 v35, v33, 16, 1
	v_add3_u32 v3, v30, v3, s31
	v_add3_u32 v34, v32, v34, s31
	v_add3_u32 v5, v31, v5, s31
	v_add3_u32 v35, v33, v35, s31
	v_lshrrev_b32_e32 v3, 16, v3
	v_lshrrev_b32_e32 v36, 16, v34
	v_and_or_b32 v34, v5, s71, v3
	v_and_or_b32 v35, v35, s71, v36
	flat_store_dwordx2 v[8:9], v[34:35] offset:2560
	global_load_dwordx4 v[34:37], v[38:39], off offset:2048 nt
	s_waitcnt vmcnt(0)
	v_bfe_u32 v3, v34, 16, 1
	v_bfe_u32 v40, v36, 16, 1
	v_bfe_u32 v5, v35, 16, 1
	v_bfe_u32 v41, v37, 16, 1
	v_add3_u32 v3, v34, v3, s31
	v_add3_u32 v40, v36, v40, s31
	v_add3_u32 v5, v35, v5, s31
	v_add3_u32 v41, v37, v41, s31
	v_lshrrev_b32_e32 v3, 16, v3
	v_lshrrev_b32_e32 v42, 16, v40
	v_and_or_b32 v40, v5, s71, v3
	v_and_or_b32 v41, v41, s71, v42
	flat_store_dwordx2 v[8:9], v[40:41] offset:3072
	global_load_dwordx4 v[38:41], v[38:39], off offset:3072 nt
	v_mov_b32_e32 v42, v11
	v_mov_b32_e32 v11, v14
	v_pk_mul_f32 v[14:15], v[42:43], v[42:43]
	s_nop 0
	v_pk_fma_f32 v[10:11], v[10:11], v[10:11], v[14:15]
	v_pk_mul_f32 v[14:15], v[18:19], v[18:19]
	v_pk_add_f32 v[10:11], v[10:11], v[12:13]
	v_pk_mul_f32 v[12:13], v[20:21], v[20:21]
	v_pk_add_f32 v[10:11], v[10:11], v[10:11] op_sel:[0,1] op_sel_hi:[1,0]
	v_pk_mov_b32 v[16:17], v[14:15], v[12:13] op_sel:[1,0]
	v_mov_b32_e32 v15, v13
	v_pk_add_f32 v[12:13], v[16:17], v[14:15]
	v_mul_f32_e32 v14, v23, v23
	v_mul_f32_e32 v16, v25, v25
	v_pk_add_f32 v[12:13], v[12:13], v[12:13] op_sel:[0,1] op_sel_hi:[1,0]
	v_pk_fma_f32 v[14:15], v[22:23], v[22:23], v[14:15] op_sel_hi:[1,1,0]
	v_pk_fma_f32 v[16:17], v[24:25], v[24:25], v[16:17] op_sel_hi:[1,1,0]
	v_mul_f32_e32 v11, v26, v26
	v_mul_f32_e32 v13, v27, v27
	v_mul_f32_e32 v15, v28, v28
	v_mul_f32_e32 v17, v29, v29
	v_pk_add_f32 v[10:11], v[10:11], v[12:13]
	v_pk_add_f32 v[12:13], v[14:15], v[16:17]
	v_pk_mul_f32 v[14:15], v[30:31], v[30:31]
	v_pk_add_f32 v[10:11], v[10:11], v[12:13]
	v_pk_mul_f32 v[12:13], v[32:33], v[32:33]
	v_pk_add_f32 v[10:11], v[10:11], v[10:11] op_sel:[0,1] op_sel_hi:[1,0]
	v_pk_mov_b32 v[16:17], v[14:15], v[12:13] op_sel:[1,0]
	v_mov_b32_e32 v15, v13
	v_pk_add_f32 v[12:13], v[16:17], v[14:15]
	v_mul_f32_e32 v14, v35, v35
	v_mul_f32_e32 v16, v37, v37
	v_pk_add_f32 v[12:13], v[12:13], v[12:13] op_sel:[0,1] op_sel_hi:[1,0]
	v_pk_fma_f32 v[14:15], v[34:35], v[34:35], v[14:15] op_sel_hi:[1,1,0]
	v_pk_fma_f32 v[16:17], v[36:37], v[36:37], v[16:17] op_sel_hi:[1,1,0]
	s_waitcnt vmcnt(0)
	v_mul_f32_e32 v11, v38, v38
	v_mul_f32_e32 v13, v39, v39
	v_mul_f32_e32 v15, v40, v40
	v_mul_f32_e32 v17, v41, v41
	v_pk_add_f32 v[10:11], v[10:11], v[12:13]
	v_pk_add_f32 v[12:13], v[14:15], v[16:17]
	s_nop 0
	v_pk_add_f32 v[10:11], v[10:11], v[12:13]
	v_bfe_u32 v12, v40, 16, 1
	v_add_f32_e32 v3, v10, v11
	ds_swizzle_b32 v5, v3 offset:swizzle(SWAP,1)
	v_bfe_u32 v10, v38, 16, 1
	v_bfe_u32 v11, v39, 16, 1
	v_bfe_u32 v13, v41, 16, 1
	v_add3_u32 v10, v38, v10, s31
	s_waitcnt lgkmcnt(0)
	v_add_f32_e32 v3, v3, v5
	ds_swizzle_b32 v5, v3 offset:swizzle(SWAP,2)
	v_add3_u32 v12, v40, v12, s31
	v_add3_u32 v11, v39, v11, s31
	v_add3_u32 v13, v41, v13, s31
	v_lshrrev_b32_e32 v10, 16, v10
	s_waitcnt lgkmcnt(0)
	v_add_f32_e32 v3, v3, v5
	ds_swizzle_b32 v5, v3 offset:swizzle(SWAP,4)
	v_lshrrev_b32_e32 v12, 16, v12
	v_and_or_b32 v10, v11, s71, v10
	v_and_or_b32 v11, v13, s71, v12
	flat_store_dwordx2 v[8:9], v[10:11] offset:3584
	s_waitcnt lgkmcnt(0)
	v_add_f32_e32 v3, v3, v5
	s_nop 1
	v_add_f32_dpp v3, v3, v3 row_mirror row_mask:0xf bank_mask:0xf
	ds_swizzle_b32 v5, v3 offset:swizzle(SWAP,16)
	s_waitcnt lgkmcnt(0)
	v_add_f32_e32 v3, v3, v5
	v_mov_b32_e32 v5, v3
	s_nop 1
	v_permlane32_swap_b32_e32 v3, v5
	v_add_f32_e32 v3, v3, v5
	s_and_saveexec_b64 s[10:11], s[40:41]
	s_cbranch_execz .LBB0_631
